# static s_setprio 1 for waves 4-7 across the mode-A tile loop (strategy 4) stacked on: mode-C range-compare masks, mode-C tile-1 loads issued with tile-0, mode-A per-tile load address strength reductio
# speedup vs baseline: 1.0148x; 1.0141x over previous
; template <int DQK, int DV, int MODE>
; __device__ __forceinline__ void attn_item(LAS unsigned char* lds, int item, const AttnCtx& cx) {
;     ...
;     auto issue = [&](int j) {
;         const int sbase = (j % NST) * SB;
; #pragma unroll
;         for (int i = 0; i < LPWMAX; ++i) {
;             const int cid = wq + 4 * i;
;             if (cid < nchh) {
;                 const bool isv = cid >= KCH; const int lc = isv ? cid - KCH : cid;
;                 const int pc = lc * 64 + lane, ppr = isv ? VP / 16 : KP / 16, row = pc / ppr, cp = pc - row * ppr;
;                 if (cp < (isv ? DV / 8 : DQK / 8)) {
;                     const bf16_t* src = P + (size_t)ktok(j, row) * NIN + (isv ? vcol : kcol) + cp * 8;
;     ...
;     if (DMA) {
; #pragma unroll
;         for (int j0 = 0; j0 < DIST; ++j0) if (j0 < ntiles) issue(j0);
;     } else gload(0);
;     bf16x8 qf[NQF];
; #pragma unroll
;     for (int ks = 0; ks < NQF; ++ks) qf[ks] = *(const bf16x8*)(P + (size_t)qtok * NIN + qcol + 16 * ks + 8 * h);
;     if (MODE == 1) { for (int i = th; i < 640; i += 256) { const int k = i - 64; biasL[i] = (k >= 0 && k < 465) ? cx.rpb[head * 465 + k] * LOG2E : 0.f; } }
;     f32x16 O[NDV];
; #pragma unroll
;     for (int d = 0; d < NDV; ++d)
; #pragma unroll
;         for (int i = 0; i < 16; ++i) O[d][i] = 0.f;
;     float mhat = 0.f; bool first = true;
;     f32x16 negm, Lacc;
; #pragma unroll
;     for (int i = 0; i < 16; ++i) { negm[i] = 0.f; Lacc[i] = 0.f; }
;     const bf16x8 ones8 = {(short)0x3F80, (short)0x3F80, (short)0x3F80, (short)0x3F80, (short)0x3F80, (short)0x3F80, (short)0x3F80, (short)0x3F80};
;     constexpr float THR = 6.f;
;     f32x16 cin0, cin1;
;     auto set_cin = [&]() {
; #pragma unroll
;         for (int i = 0; i < 16; ++i) {
;             const int ck0 = crow(i, h), ck1 = ck0 + 32;
;             cin0[i] = (((ck0 >= na_csq) && (ck0 < na_csq + 16)) ? 0.f : NEGBIG) - mhat;
;             cin1[i] = (((ck1 >= na_csq) && (ck1 < na_csq + 16)) ? 0.f : NEGBIG) - mhat;
;         }
;     };
;     if (MODE == 1) set_cin();
; #pragma unroll
;     for (int ks = 0; ks < NQF; ++ks) asm volatile("" : "+v"(qf[ks]));
;     if (!DMA) { lstore(0); __syncthreads(); }
;     else if (MODE == 1) __syncthreads();
;     const int q4 = (lane & 15) >> 2, p4 = lane & 3, rblk = (lane >> 4) & 1;
;     bf16x8 pa[2][2];
;     s16x4 vlo[2][4], vhi[2][4];
;     f32x16 s0, s1;
.LBB0_199:
	s_or_b64 exec, exec, s[68:69]
	s_lshl_b32 s48, s30, 5
	v_and_b32_e32 v201, 31, v16
	s_or_b32 s48, s52, s48
	v_or_b32_e32 v180, s48, v201
	v_mov_b64_e32 v[24:25], s[86:87]
	v_lshrrev_b32_e32 v23, 5, v17
	v_mad_i64_i32 v[182:183], s[68:69], v180, s33, v[24:25]
	s_ashr_i32 s67, s66, 31
	v_lshl_add_u64 v[24:25], s[66:67], 1, v[182:183]
	v_lshlrev_b32_e32 v0, 4, v23
	v_lshl_add_u64 v[24:25], v[24:25], 0, v[0:1]
	global_load_dwordx4 v[146:149], v[24:25], off
	global_load_dwordx4 v[150:153], v[24:25], off offset:32
	global_load_dwordx4 v[154:157], v[24:25], off offset:64
	global_load_dwordx4 v[158:161], v[24:25], off offset:96
	s_xor_b32 s48, s30, 3
	v_mul_f32_e32 v22, v21, v22
	s_lshr_b32 s81, s37, 6
	s_add_i32 s48, s48, s53
	v_trunc_f32_e32 v22, v22
	s_and_b64 s[52:53], s[64:65], exec
	v_fma_f32 v21, -v22, v19, v21
	v_cvt_i32_f32_e32 v22, v22
	s_cselect_b32 s83, 64, 32
	s_lshr_b32 s84, s48, 2
	s_lshl_b64 s[44:45], s[44:45], 1
	s_lshl_b32 s48, s51, 1
	s_add_i32 s97, s74, s50
	s_and_b32 s50, s37, 0xffc0
	s_and_b32 s51, s37, 0xc0
	s_movk_i32 s4, 0x90
	v_cmp_ge_f32_e64 vcc, |v21|, v19
	v_lshl_add_u64 v[184:185], v[2:3], 0, s[44:45]
	v_lshl_add_u64 v[188:189], v[6:7], 0, s[48:49]
	v_lshl_add_u64 v[190:191], v[8:9], 0, s[48:49]
	v_lshl_add_u64 v[192:193], v[10:11], 0, s[48:49]
	v_lshl_add_u64 v[194:195], v[12:13], 0, s[48:49]
	v_lshl_add_u64 v[196:197], v[14:15], 0, s[48:49]
	v_bitop3_b16 v2, s50, v16, 63 bitop3:0xf8
	v_mov_b32_e32 v3, s51
	s_movk_i32 s48, 0x100
	v_mad_u32_u24 v202, v201, s4, v0
	v_cndmask_b32_e32 v19, 0, v20, vcc
	v_lshl_add_u64 v[186:187], v[4:5], 0, s[44:45]
	s_add_i32 s44, s51, 0x4c0
	v_and_b32_e32 v2, 0xff, v2
	v_bitop3_b16 v3, v17, s48, v3 bitop3:0xfe
	s_mov_b32 s4, 0x1c71c71d
	v_bitop3_b16 v4, s44, v16, 63 bitop3:0xf8
	v_add_u32_e32 v6, v22, v19
	v_mul_hi_u32 v2, v2, s4
	v_and_b32_e32 v3, 0xffff, v3
	v_and_b32_e32 v4, 0xffff, v4
	v_bfe_i32 v6, v6, 0, 11
	v_or_b32_e32 v204, 0xc0, v2
	v_mul_hi_u32 v2, v3, s4
	s_mov_b32 s4, 0xccccccd
	v_mul_hi_u32 v3, v4, s4
	v_mul_i32_i24_e32 v4, s36, v6
	s_add_i32 s45, s51, 0x3c0
	v_or_b32_e32 v206, 0xc0, v2
	v_sub_u32_e32 v2, v18, v4
	v_bitop3_b16 v5, s45, v16, 63 bitop3:0xf8
	v_cmp_gt_i32_e64 s[44:45], s3, v2
	v_lshlrev_b32_e32 v2, 3, v2
	v_add_u32_e32 v207, 0xc0, v3
	v_ashrrev_i32_e32 v3, 31, v2
	v_lshl_add_u64 v[198:199], v[2:3], 1, s[46:47]
	v_and_b32_e32 v2, 0xffff, v5
	v_mul_hi_u32 v2, v2, s4
	s_add_i32 s3, s51, 0x2c0
	v_add_u32_e32 v208, 0xc0, v2
	v_bitop3_b16 v2, s3, v16, 63 bitop3:0xf8
	v_and_b32_e32 v2, 0xffff, v2
	v_mul_hi_u32 v2, v2, s4
	s_add_i32 s3, s51, 0x1c0
	v_or_b32_e32 v209, 0xc0, v2
	v_bitop3_b16 v2, s3, v16, 63 bitop3:0xf8
	v_and_b32_e32 v2, 0xffff, v2
	v_mul_hi_u32 v2, v2, s4
	s_addk_i32 s51, 0xc0
	v_lshrrev_b32_e32 v24, 2, v16
	v_lshlrev_b32_e32 v200, 2, v23
	v_or_b32_e32 v210, 0xc0, v2
	v_bitop3_b16 v2, s51, v16, 63 bitop3:0xf8
	v_lshlrev_b32_e32 v25, 1, v16
	v_lshlrev_b32_e32 v26, 3, v16
	v_and_or_b32 v24, v24, 3, v200
	v_and_b32_e32 v2, 0xffff, v2
	v_and_b32_e32 v23, 32, v25
	v_and_b32_e32 v25, 24, v26
	v_mul_u32_u24_e32 v24, 0x140, v24
	v_mul_hi_u32 v2, v2, s4
	v_mov_b32_e32 v50, v1
	v_mov_b32_e32 v51, v1
	v_mov_b32_e32 v64, v1
	v_mov_b32_e32 v65, v1
	v_or3_b32 v203, v23, v25, v24
	v_add_u32_e32 v205, 0xc0, v6
	v_or_b32_e32 v211, 0xc0, v2
	v_mov_b32_e32 v52, v1
	v_mov_b32_e32 v53, v1
	v_mov_b32_e32 v54, v1
	v_mov_b32_e32 v55, v1
	v_mov_b32_e32 v56, v1
	v_mov_b32_e32 v57, v1
	v_mov_b32_e32 v58, v1
	v_mov_b32_e32 v59, v1
	v_mov_b32_e32 v60, v1
	v_mov_b32_e32 v61, v1
	v_mov_b32_e32 v62, v1
	v_mov_b32_e32 v63, v1
	v_mov_b32_e32 v212, 0
	v_mov_b64_e32 v[34:35], v[50:51]
	v_mov_b64_e32 v[18:19], v[50:51]
	v_mov_b64_e32 v[2:3], v[50:51]
	v_mov_b64_e32 v[80:81], v[64:65]
	s_mov_b32 s82, 0
	v_ashrrev_i32_e32 v181, 31, v180
	s_add_i32 s85, s70, 0
	s_add_i32 s93, s71, 0
	s_add_i32 s94, s89, 0
	s_add_i32 s95, s90, 0
	s_add_i32 s96, s91, 0
	s_add_i32 s52, s83, -2
	s_mov_b64 s[64:65], -1
	v_mov_b64_e32 v[36:37], v[52:53]
	v_mov_b64_e32 v[38:39], v[54:55]
	v_mov_b64_e32 v[40:41], v[56:57]
	v_mov_b64_e32 v[42:43], v[58:59]
	v_mov_b64_e32 v[44:45], v[60:61]
	v_mov_b64_e32 v[46:47], v[62:63]
	v_mov_b64_e32 v[48:49], v[64:65]
	v_mov_b64_e32 v[20:21], v[52:53]
	v_mov_b64_e32 v[22:23], v[54:55]
	v_mov_b64_e32 v[24:25], v[56:57]
	v_mov_b64_e32 v[26:27], v[58:59]
	v_mov_b64_e32 v[28:29], v[60:61]
	v_mov_b64_e32 v[30:31], v[62:63]
	v_mov_b64_e32 v[32:33], v[64:65]
	v_mov_b64_e32 v[4:5], v[52:53]
	v_mov_b64_e32 v[6:7], v[54:55]
	v_mov_b64_e32 v[8:9], v[56:57]
	v_mov_b64_e32 v[10:11], v[58:59]
	v_mov_b64_e32 v[12:13], v[60:61]
	v_mov_b64_e32 v[14:15], v[62:63]
	v_mov_b64_e32 v[16:17], v[64:65]
	v_mov_b64_e32 v[78:79], v[62:63]
	v_mov_b64_e32 v[76:77], v[60:61]
	v_mov_b64_e32 v[74:75], v[58:59]
	v_mov_b64_e32 v[72:73], v[56:57]
	v_mov_b64_e32 v[70:71], v[54:55]
	v_mov_b64_e32 v[68:69], v[52:53]
	v_mov_b64_e32 v[66:67], v[50:51]
	v_mov_b32_e32 v114, 0
	v_mov_b32_e32 v115, v212
	v_mov_b32_e32 v116, v212
	v_mov_b32_e32 v117, v212
	v_mov_b32_e32 v118, v212
	v_mov_b32_e32 v119, v212
	v_mov_b32_e32 v120, v212
	v_mov_b32_e32 v121, v212
	v_mov_b32_e32 v122, v212
	v_mov_b32_e32 v123, v212
	v_mov_b32_e32 v124, v212
	v_mov_b32_e32 v125, v212
	v_mov_b32_e32 v126, v212
	v_mov_b32_e32 v127, v212
	v_mov_b32_e32 v128, v212
	v_mov_b32_e32 v129, v212
	s_waitcnt vmcnt(0)
	v_mad_i64_i32 v[196:197], s[50:51], v207, s33, v[196:197]
	v_mad_i64_i32 v[184:185], s[50:51], v204, s33, v[184:185]
	v_mad_i64_i32 v[186:187], s[50:51], v206, s33, v[186:187]
	v_mad_i64_i32 v[198:199], s[50:51], v205, s33, v[198:199]
	v_mad_i64_i32 v[188:189], s[50:51], v211, s33, v[188:189]
	v_mad_i64_i32 v[190:191], s[50:51], v210, s33, v[190:191]
	v_mad_i64_i32 v[192:193], s[50:51], v209, s33, v[192:193]
	v_mad_i64_i32 v[194:195], s[50:51], v208, s33, v[194:195]
	s_cmpk_gt_u32 s37, 0xff
	s_cbranch_scc0 .Lprio_skip
	s_setprio 1
.Lprio_skip:
	s_branch .LBB0_201
.LBB0_200:
	s_add_i32 s97, s97, 64
	s_cmp_eq_u32 s82, s83
	s_mov_b64 s[64:65], 0
	s_cbranch_scc1 .LBB0_268

; #define LAS __attribute__((address_space(3)))
; #define SBAR() __builtin_amdgcn_sched_barrier(0)
; template <int DQK, int DV, int MODE>
; __device__ __forceinline__ void attn_item(LAS unsigned char* lds, int item, const AttnCtx& cx) {
;     ...
;     auto issue = [&](int j) {
;         const int sbase = (j % NST) * SB;
; #pragma unroll
;         for (int i = 0; i < LPWMAX; ++i) {
;             const int cid = wq + 4 * i;
;             if (cid < nchh) {
;                 const bool isv = cid >= KCH; const int lc = isv ? cid - KCH : cid;
;                 const int pc = lc * 64 + lane, ppr = isv ? VP / 16 : KP / 16, row = pc / ppr, cp = pc - row * ppr;
;                 if (cp < (isv ? DV / 8 : DQK / 8)) {
;                     const bf16_t* src = P + (size_t)ktok(j, row) * NIN + (isv ? vcol : kcol) + cp * 8;
;                     __builtin_amdgcn_global_load_lds((const unsigned*)src, (LAS unsigned*)(lds + sbase + (isv ? voff : koff) + lc * 1024), 16, 0, 0);
;     ...
;     for (int j = 0; j < ntiles; ++j) {
;         if (DMA) {
;             wait_vm(n_w * max(min(DIST - 1 - WAHEAD, ntiles - 1 - j - WAHEAD), 0));
;             __builtin_amdgcn_s_barrier();
;             SBAR();
;             if (j + DIST < ntiles) issue(j + DIST);
.LBB0_232:
	s_barrier
	s_add_i32 s3, s82, 3
	s_cmp_ge_u32 s3, s83
	s_cbranch_scc1 .LBB0_243
	s_and_b32 s3, s3, 3
	s_mul_i32 s3, s3, 0x9800
	s_mul_i32 s50, s97, s33
	s_mov_b32 s51, 0
	s_and_saveexec_b64 s[46:47], s[38:39]
	s_cbranch_execnz .LBB0_259
	s_or_b64 exec, exec, s[46:47]
	s_and_saveexec_b64 s[46:47], s[40:41]
	s_cbranch_execnz .LBB0_260

; #define LAS __attribute__((address_space(3)))
; template <int DQK, int DV, int MODE>
; __device__ __forceinline__ void attn_item(LAS unsigned char* lds, int item, const AttnCtx& cx) {
;     ...
;                 const int pc = lc * 64 + lane, ppr = isv ? VP / 16 : KP / 16, row = pc / ppr, cp = pc - row * ppr;
;                 if (cp < (isv ? DV / 8 : DQK / 8)) {
;                     const bf16_t* src = P + (size_t)ktok(j, row) * NIN + (isv ? vcol : kcol) + cp * 8;
;                     __builtin_amdgcn_global_load_lds((const unsigned*)src, (LAS unsigned*)(lds + sbase + (isv ? voff : koff) + lc * 1024), 16, 0, 0);
.LBB0_241:
	s_add_i32 s3, s96, s3
	v_lshl_add_u64 v[130:131], v[196:197], 0, s[50:51]
	s_add_i32 m0, s3, 0x4800
	s_nop 0
	global_load_lds_dwordx4 v[130:131], off

; #define LAS __attribute__((address_space(3)))
; template <int DQK, int DV, int MODE>
; __device__ __forceinline__ void attn_item(LAS unsigned char* lds, int item, const AttnCtx& cx) {
;     ...
;                 const int pc = lc * 64 + lane, ppr = isv ? VP / 16 : KP / 16, row = pc / ppr, cp = pc - row * ppr;
;                 if (cp < (isv ? DV / 8 : DQK / 8)) {
;                     const bf16_t* src = P + (size_t)ktok(j, row) * NIN + (isv ? vcol : kcol) + cp * 8;
;                     __builtin_amdgcn_global_load_lds((const unsigned*)src, (LAS unsigned*)(lds + sbase + (isv ? voff : koff) + lc * 1024), 16, 0, 0);
.LBB0_259:
	v_lshl_add_u64 v[130:131], v[184:185], 0, s[50:51]
	s_add_i32 m0, s78, s3
	s_nop 0
	global_load_lds_dwordx4 v[130:131], off
	s_or_b64 exec, exec, s[46:47]
	s_and_saveexec_b64 s[46:47], s[40:41]
	s_cbranch_execz .LBB0_235
.LBB0_260:
	v_lshl_add_u64 v[130:131], v[186:187], 0, s[50:51]
	s_add_i32 m0, s79, s3
	s_nop 0
	global_load_lds_dwordx4 v[130:131], off
	s_or_b64 exec, exec, s[46:47]
	s_and_b64 vcc, exec, s[42:43]
	s_cbranch_vccnz .LBB0_236
.LBB0_261:
	s_and_saveexec_b64 s[46:47], s[44:45]
	s_cbranch_execz .LBB0_263
	v_lshl_add_u64 v[130:131], v[198:199], 0, s[50:51]
	s_add_i32 m0, s80, s3
	s_nop 0
	global_load_lds_dwordx4 v[130:131], off

; #define LAS __attribute__((address_space(3)))
; template <int DQK, int DV, int MODE>
; __device__ __forceinline__ void attn_item(LAS unsigned char* lds, int item, const AttnCtx& cx) {
;     ...
;     auto issue = [&](int j) {
;         const int sbase = (j % NST) * SB;
; #pragma unroll
;         for (int i = 0; i < LPWMAX; ++i) {
;             const int cid = wq + 4 * i;
;             if (cid < nchh) {
;                 const bool isv = cid >= KCH; const int lc = isv ? cid - KCH : cid;
;                 const int pc = lc * 64 + lane, ppr = isv ? VP / 16 : KP / 16, row = pc / ppr, cp = pc - row * ppr;
;                 if (cp < (isv ? DV / 8 : DQK / 8)) {
;                     const bf16_t* src = P + (size_t)ktok(j, row) * NIN + (isv ? vcol : kcol) + cp * 8;
;                     __builtin_amdgcn_global_load_lds((const unsigned*)src, (LAS unsigned*)(lds + sbase + (isv ? voff : koff) + lc * 1024), 16, 0, 0);
;                 }
;             }
;         }
;     };
;     ...
;     const float lt = Lacc[0];
;     const float inv = 1.f / lt;
;     if (DMA) __syncthreads();
;     if (MODE == 0) {
;         LAS float* X = (LAS float*)lds;
;         if (hf == 1) {
; #pragma unroll
;             for (int d = 0; d < NDV; ++d)
; #pragma unroll
;                 for (int g4 = 0; g4 < 4; ++g4) {
;                     f32x4 v = {O[d][4 * g4] * inv, O[d][4 * g4 + 1] * inv, O[d][4 * g4 + 2] * inv, O[d][4 * g4 + 3] * inv};
;                     *(LAS f32x4*)(X + (32 * wq + r) * 132 + 32 * d + 8 * g4 + 4 * h) = v;
;                 }
;         }
.LBB0_264:
	s_add_i32 s36, s85, s3
	v_lshl_add_u64 v[130:131], v[188:189], 0, s[50:51]
	s_add_i32 m0, s36, 0x4800
	s_nop 0
	global_load_lds_dwordx4 v[130:131], off
	s_or_b64 exec, exec, s[46:47]
	s_and_saveexec_b64 s[46:47], s[56:57]
	s_cbranch_execz .LBB0_238
.LBB0_265:
	s_add_i32 s36, s93, s3
	v_lshl_add_u64 v[130:131], v[190:191], 0, s[50:51]
	s_add_i32 m0, s36, 0x4800
	s_nop 0
	global_load_lds_dwordx4 v[130:131], off
	s_or_b64 exec, exec, s[46:47]
	s_and_saveexec_b64 s[46:47], s[58:59]
	s_cbranch_execz .LBB0_239
.LBB0_266:
	s_add_i32 s36, s94, s3
	v_lshl_add_u64 v[130:131], v[192:193], 0, s[50:51]
	s_add_i32 m0, s36, 0x4800
	s_nop 0
	global_load_lds_dwordx4 v[130:131], off
	s_or_b64 exec, exec, s[46:47]
	s_and_saveexec_b64 s[46:47], s[60:61]
	s_cbranch_execz .LBB0_240
.LBB0_267:
	s_add_i32 s36, s95, s3
	v_lshl_add_u64 v[130:131], v[194:195], 0, s[50:51]
	s_add_i32 m0, s36, 0x4800
	s_nop 0
	global_load_lds_dwordx4 v[130:131], off
	s_or_b64 exec, exec, s[46:47]
	s_and_saveexec_b64 s[46:47], s[62:63]
	s_cbranch_execnz .LBB0_241
	s_branch .LBB0_242
.LBB0_268:
	s_setprio 0
	v_div_scale_f32 v67, s[22:23], v66, v66, 1.0
	v_rcp_f32_e32 v68, v67
	v_div_scale_f32 v69, vcc, 1.0, v66, 1.0
	s_waitcnt vmcnt(0) lgkmcnt(0)
	v_fma_f32 v70, -v67, v68, 1.0
	v_fmac_f32_e32 v68, v70, v68
	v_mul_f32_e32 v70, v69, v68
	v_fma_f32 v71, -v67, v70, v69
	v_fmac_f32_e32 v70, v71, v68
	v_fma_f32 v67, -v67, v70, v69
	v_div_fmas_f32 v67, v67, v68, v70
	v_div_fixup_f32 v136, v67, v66, 1.0
	s_and_b64 vcc, exec, s[46:47]
	s_barrier
	s_cbranch_vccnz .LBB0_270
	v_lshl_or_b32 v66, s30, 5, v201
	v_mul_u32_u24_e32 v66, 0x210, v66
	v_add3_u32 v70, 0, v66, v0
	v_pk_mul_f32 v[66:67], v[136:137], v[50:51] op_sel_hi:[0,1]
	v_pk_mul_f32 v[68:69], v[136:137], v[52:53] op_sel_hi:[0,1]
	ds_write_b128 v70, v[66:69]
	v_pk_mul_f32 v[66:67], v[136:137], v[54:55] op_sel_hi:[0,1]
	v_pk_mul_f32 v[68:69], v[136:137], v[56:57] op_sel_hi:[0,1]
	ds_write_b128 v70, v[66:69] offset:32
	v_pk_mul_f32 v[66:67], v[136:137], v[58:59] op_sel_hi:[0,1]
	v_pk_mul_f32 v[68:69], v[136:137], v[60:61] op_sel_hi:[0,1]
	ds_write_b128 v70, v[66:69] offset:64
	v_pk_mul_f32 v[66:67], v[136:137], v[62:63] op_sel_hi:[0,1]
	v_pk_mul_f32 v[68:69], v[136:137], v[64:65] op_sel_hi:[0,1]
	ds_write_b128 v70, v[66:69] offset:96
	v_pk_mul_f32 v[66:67], v[136:137], v[34:35] op_sel_hi:[0,1]
	v_pk_mul_f32 v[68:69], v[136:137], v[36:37] op_sel_hi:[0,1]
	ds_write_b128 v70, v[66:69] offset:128
	v_pk_mul_f32 v[66:67], v[136:137], v[38:39] op_sel_hi:[0,1]
	v_pk_mul_f32 v[68:69], v[136:137], v[40:41] op_sel_hi:[0,1]
	ds_write_b128 v70, v[66:69] offset:160
	v_pk_mul_f32 v[66:67], v[136:137], v[42:43] op_sel_hi:[0,1]
	v_pk_mul_f32 v[68:69], v[136:137], v[44:45] op_sel_hi:[0,1]
	ds_write_b128 v70, v[66:69] offset:192
	v_pk_mul_f32 v[66:67], v[136:137], v[46:47] op_sel_hi:[0,1]
	v_pk_mul_f32 v[68:69], v[136:137], v[48:49] op_sel_hi:[0,1]
	ds_write_b128 v70, v[66:69] offset:224
	v_pk_mul_f32 v[66:67], v[136:137], v[18:19] op_sel_hi:[0,1]
	v_pk_mul_f32 v[68:69], v[136:137], v[20:21] op_sel_hi:[0,1]
	ds_write_b128 v70, v[66:69] offset:256
	v_pk_mul_f32 v[66:67], v[136:137], v[22:23] op_sel_hi:[0,1]
	v_pk_mul_f32 v[68:69], v[136:137], v[24:25] op_sel_hi:[0,1]
	ds_write_b128 v70, v[66:69] offset:288
	v_pk_mul_f32 v[66:67], v[136:137], v[26:27] op_sel_hi:[0,1]
	v_pk_mul_f32 v[68:69], v[136:137], v[28:29] op_sel_hi:[0,1]
	ds_write_b128 v70, v[66:69] offset:320
	v_pk_mul_f32 v[66:67], v[136:137], v[30:31] op_sel_hi:[0,1]
	v_pk_mul_f32 v[68:69], v[136:137], v[32:33] op_sel_hi:[0,1]
	ds_write_b128 v70, v[66:69] offset:352
	v_pk_mul_f32 v[66:67], v[136:137], v[2:3] op_sel_hi:[0,1]
	v_pk_mul_f32 v[68:69], v[136:137], v[4:5] op_sel_hi:[0,1]
	ds_write_b128 v70, v[66:69] offset:384
	v_pk_mul_f32 v[66:67], v[136:137], v[6:7] op_sel_hi:[0,1]
	v_pk_mul_f32 v[68:69], v[136:137], v[8:9] op_sel_hi:[0,1]
	ds_write_b128 v70, v[66:69] offset:416
	v_pk_mul_f32 v[66:67], v[136:137], v[10:11] op_sel_hi:[0,1]
	v_pk_mul_f32 v[68:69], v[136:137], v[12:13] op_sel_hi:[0,1]
	ds_write_b128 v70, v[66:69] offset:448
	v_pk_mul_f32 v[66:67], v[136:137], v[14:15] op_sel_hi:[0,1]
	v_pk_mul_f32 v[68:69], v[136:137], v[16:17] op_sel_hi:[0,1]
	ds_write_b128 v70, v[66:69] offset:480

; template <int DQK, int DV, int MODE>
; __device__ __forceinline__ void attn_item(LAS unsigned char* lds, int item, const AttnCtx& cx) {
;     ...
;         const int unit = item * 2 + hf, nbk = cx.n >> 7; head = unit / nbk; const int blk = unit - head * nbk; tok0 = blk * 128; S = seq_len_of(cx.row0 + tok0); seqbase = ((cx.row0 + tok0) & ~(S - 1)) - cx.row0;
;         qcol = COL_C_Q + head * 128; kcol = COL_C_K + head * 128; vcol = COL_C_V + head * 128; ntiles = 4;
;         c_dlog = 2 * (head >> 2); const int b = (tok0 - seqbase) >> 7; c_rho = b & ((1 << c_dlog) - 1); c_l0 = (b >> c_dlog) * 128; c_L = S >> c_dlog;
;         c_lq = c_l0 + 32 * wq + r; qtok = seqbase + (c_lq << c_dlog) + c_rho;
;     }
;     auto ktok = [&](int j, int kr) -> int {
;         if (MODE == 0) return seqbase + 64 * j + kr;
;         if (MODE == 1) return seqbase + min(na_rs0 + j, na_rows - 1) * 64 + kr;
;         const int lk = min(max(c_l0 - 64 + 64 * j + kr, 0), c_L - 1); return seqbase + (lk << c_dlog) + c_rho;
;     ...
;     auto gload = [&](int j) {
; #pragma unroll
;         for (int i = 0; i < NKP; ++i) { const int pid = th + 256 * i, row = pid / KPR, cp = pid % KPR; kreg[DMA ? 0 : i] = *(const u32x4*)(P + (size_t)ktok(j, row) * NIN + kcol + cp * 8); }
;         if (loadV) {
; #pragma unroll
;             for (int i = 0; i < NVP; ++i) { const int pid = th + 256 * i, row = pid / VPR, cp = pid % VPR; vreg[DMA ? 0 : i] = *(const u32x4*)(P + (size_t)ktok(j, row) * NIN + vcol + cp * 8); }
;         }
;     };
;     auto lstore = [&](int b) {
;         LAS unsigned char* base = lds + b * SB;
; #pragma unroll
;         for (int i = 0; i < NKP; ++i) { const int pid = th + 256 * i, row = pid / KPR, cp = pid % KPR; *(LAS u32x4*)(base + koff + row * KP + cp * 16) = kreg[DMA ? 0 : i]; }
;         if (loadV) {
; #pragma unroll
;             for (int i = 0; i < NVP; ++i) { const int pid = th + 256 * i, row = pid / VPR, cp = pid % VPR; *(LAS u32x4*)(base + voff + row * VP + cp * 16) = vreg[DMA ? 0 : i]; }
;         }
;     };
;     LAS float* biasL = (LAS float*)(lds + NST * SB) + hf * 640;
;     if (DMA) {
; #pragma unroll
;         for (int j0 = 0; j0 < DIST; ++j0) if (j0 < ntiles) issue(j0);
;     } else gload(0);
;     bf16x8 qf[NQF];
; #pragma unroll
;     for (int ks = 0; ks < NQF; ++ks) qf[ks] = *(const bf16x8*)(P + (size_t)qtok * NIN + qcol + 16 * ks + 8 * h);
.LBB0_294:
	v_mov_b32_e32 v116, v251
	v_readlane_b32 s5, v255, 24
	v_readfirstlane_b32 s0, v116
	s_ashr_i32 s43, s0, 6
	s_ashr_i32 s52, s0, 8
	s_lshl_b32 s0, s63, 1
	s_add_i32 s0, s52, s0
	s_abs_i32 s22, s0
	s_mul_hi_u32 s23, s22, s62
	s_mul_i32 s24, s23, s48
	s_sub_i32 s22, s22, s24
	s_and_b32 s1, s43, 3
	s_ashr_i32 s3, s0, 31
	s_add_i32 s24, s23, 1
	s_sub_i32 s25, s22, s48
	s_cmp_ge_u32 s22, s48
	s_cselect_b32 s23, s24, s23
	s_cselect_b32 s22, s25, s22
	s_add_i32 s24, s23, 1
	s_cmp_ge_u32 s22, s48
	s_cselect_b32 s22, s24, s23
	s_xor_b32 s22, s22, s3
	s_sub_i32 s42, s22, s3
	s_lshl_b32 s3, s42, s37
	s_sub_i32 s0, s0, s3
	s_lshl_b32 s0, s0, 7
	s_add_i32 s3, s0, s5
	s_cmpk_lt_i32 s3, 0x4000
	s_movk_i32 s4, 0xf000
	s_cselect_b32 s22, s4, 0xfffff800
	s_movk_i32 s4, 0x1000
	s_cselect_b32 s23, s4, 0x800
	s_and_b32 s3, s22, s3
	s_sub_i32 s3, s3, s5
	s_ashr_i32 s25, s42, 1
	s_and_b32 s64, s25, -2
	s_sub_i32 s0, s0, s3
	s_ashr_i32 s0, s0, 7
	s_lshl_b32 s25, -1, s64
	s_andn2_b32 s65, s0, s25
	s_ashr_i32 s0, s0, s64
	s_lshl_b32 s67, s0, 7
	s_lshl_b32 s30, s1, 5
	v_and_b32_e32 v228, 31, v116
	s_or_b32 s66, s67, s30
	v_or_b32_e32 v0, s66, v228
	v_bfe_u32 v41, v116, 4, 4
	v_lshlrev_b32_e32 v2, s64, v0
	s_add_i32 s65, s65, s3
	s_sub_i32 s0, s67, 64
	v_or_b32_e32 v229, s67, v41
	s_lshr_b32 s68, s23, s64
	v_add_u32_e32 v227, s65, v2
	v_lshrrev_b32_e32 v20, 4, v116
	v_or_b32_e32 v2, s0, v41
	v_subrev_u32_e32 v10, 32, v229
	v_max_i32_e32 v2, 0, v2
	s_add_i32 s69, s68, -1
	v_max_i32_e32 v10, 0, v10
	v_or_b32_e32 v20, -16, v20
	s_lshl_b32 s22, s42, 7
	v_min_i32_e32 v2, s69, v2
	v_subrev_u32_e32 v6, 48, v229
	v_min_i32_e32 v10, s69, v10
	v_add_u32_e32 v20, s67, v20
	s_add_i32 s24, s22, 0x1200
	s_add_i32 s38, s22, 0x1800
	v_lshlrev_b32_e32 v2, s64, v2
	v_max_i32_e32 v6, 0, v6
	v_lshlrev_b32_e32 v10, s64, v10
	v_max_i32_e32 v20, 0, v20
	v_add_u32_e32 v2, s65, v2
	v_mov_b64_e32 v[34:35], s[86:87]
	s_ashr_i32 s25, s24, 31
	v_min_i32_e32 v6, s69, v6
	v_add_u32_e32 v10, s65, v10
	v_min_i32_e32 v20, s69, v20
	s_ashr_i32 s39, s38, 31
	v_and_b32_e32 v117, 15, v116
	v_mad_i64_i32 v[14:15], s[40:41], v2, s33, v[34:35]
	s_lshl_b64 s[44:45], s[24:25], 1
	v_lshlrev_b32_e32 v6, s64, v6
	v_mad_i64_i32 v[18:19], s[24:25], v10, s33, v[34:35]
	v_lshlrev_b32_e32 v20, s64, v20
	s_lshl_b64 s[46:47], s[38:39], 1
	v_lshl_add_u64 v[2:3], v[14:15], 0, s[44:45]
	v_lshlrev_b32_e32 v212, 4, v117
	v_mov_b32_e32 v213, v1
	v_add_u32_e32 v6, s65, v6
	v_lshl_add_u64 v[10:11], v[18:19], 0, s[44:45]
	v_add_u32_e32 v20, s65, v20
	v_lshl_add_u64 v[14:15], v[14:15], 0, s[46:47]
	v_mad_i64_i32 v[16:17], s[24:25], v6, s33, v[34:35]
	v_lshl_add_u64 v[10:11], v[10:11], 0, v[212:213]
	v_mad_i64_i32 v[36:37], s[24:25], v20, s33, v[34:35]
	v_lshl_add_u64 v[14:15], v[14:15], 0, v[212:213]
	global_load_dwordx4 v[10:13], v[10:11], off
	v_lshl_add_u64 v[20:21], v[36:37], 0, s[44:45]
	global_load_dwordx4 v[30:33], v[14:15], off
	v_lshl_add_u64 v[14:15], v[16:17], 0, s[46:47]
	v_lshl_add_u64 v[20:21], v[20:21], 0, v[212:213]
	v_lshl_add_u64 v[14:15], v[14:15], 0, v[212:213]
	global_load_dwordx4 v[22:25], v[20:21], off
	global_load_dwordx4 v[26:29], v[14:15], off
	v_lshl_add_u64 v[14:15], v[18:19], 0, s[46:47]
	v_lshl_add_u64 v[14:15], v[14:15], 0, v[212:213]
	v_bfe_u32 v40, v116, 5, 1
	global_load_dwordx4 v[18:21], v[14:15], off
	v_lshl_add_u64 v[14:15], v[36:37], 0, s[46:47]
	v_mad_i64_i32 v[36:37], s[24:25], v227, s33, v[34:35]
	s_ashr_i32 s23, s22, 31
	v_lshl_add_u64 v[36:37], s[22:23], 1, v[36:37]
	v_lshlrev_b32_e32 v214, 4, v40
	v_mov_b32_e32 v215, v1
	v_lshl_add_u64 v[36:37], v[36:37], 0, v[214:215]
	s_mov_b64 s[24:25], 0x1800
	v_lshl_add_u64 v[6:7], v[16:17], 0, s[44:45]
	v_lshl_add_u64 v[38:39], v[36:37], 0, s[24:25]
	v_add_co_u32_e32 v36, vcc, s4, v36
	v_lshl_add_u64 v[2:3], v[2:3], 0, v[212:213]
	v_lshl_add_u64 v[6:7], v[6:7], 0, v[212:213]
	v_lshl_add_u64 v[14:15], v[14:15], 0, v[212:213]
	v_addc_co_u32_e32 v37, vcc, 0, v37, vcc
	global_load_dwordx4 v[2:5], v[2:3], off
	s_mul_i32 s52, s52, 0x9400
	global_load_dwordx4 v[6:9], v[6:7], off
	s_add_i32 s70, s52, 0
	global_load_dwordx4 v[14:17], v[14:15], off
	s_nop 0
	global_load_dwordx4 v[144:147], v[36:37], off offset:2048
	global_load_dwordx4 v[148:151], v[38:39], off offset:32
	global_load_dwordx4 v[152:155], v[38:39], off offset:64
	global_load_dwordx4 v[156:159], v[38:39], off offset:96
	global_load_dwordx4 v[160:163], v[38:39], off offset:128
	global_load_dwordx4 v[164:167], v[38:39], off offset:160
	global_load_dwordx4 v[168:171], v[38:39], off offset:192
	global_load_dwordx4 v[172:175], v[38:39], off offset:224
	v_mul_u32_u24_e32 v230, 0x110, v41
	v_add3_u32 v36, s70, v230, v212
	v_max_i32_e32 v178, 0, v229
	v_min_i32_e32 v178, s69, v178
	v_lshlrev_b32_e32 v178, s64, v178
	v_add_u32_e32 v178, s65, v178
	v_mad_i64_i32 v[192:193], s[40:41], v178, s33, v[34:35]
	v_lshl_add_u64 v[176:177], v[192:193], 0, s[44:45]
	v_lshl_add_u64 v[192:193], v[192:193], 0, s[46:47]
	v_lshl_add_u64 v[176:177], v[176:177], 0, v[212:213]
	v_lshl_add_u64 v[192:193], v[192:193], 0, v[212:213]
	global_load_dwordx4 v[176:179], v[176:177], off
	global_load_dwordx4 v[192:195], v[192:193], off
	v_or_b32_e32 v182, 16, v229
	v_max_i32_e32 v182, 0, v182
	v_min_i32_e32 v182, s69, v182
	v_lshlrev_b32_e32 v182, s64, v182
	v_add_u32_e32 v182, s65, v182
	v_mad_i64_i32 v[196:197], s[40:41], v182, s33, v[34:35]
	v_lshl_add_u64 v[180:181], v[196:197], 0, s[44:45]
	v_lshl_add_u64 v[196:197], v[196:197], 0, s[46:47]
	v_lshl_add_u64 v[180:181], v[180:181], 0, v[212:213]
	v_lshl_add_u64 v[196:197], v[196:197], 0, v[212:213]
	global_load_dwordx4 v[180:183], v[180:181], off
	global_load_dwordx4 v[196:199], v[196:197], off
	v_or_b32_e32 v186, 32, v229
	v_max_i32_e32 v186, 0, v186
	v_min_i32_e32 v186, s69, v186
	v_lshlrev_b32_e32 v186, s64, v186
	v_add_u32_e32 v186, s65, v186
	v_mad_i64_i32 v[200:201], s[40:41], v186, s33, v[34:35]
	v_lshl_add_u64 v[184:185], v[200:201], 0, s[44:45]
	v_lshl_add_u64 v[200:201], v[200:201], 0, s[46:47]
	v_lshl_add_u64 v[184:185], v[184:185], 0, v[212:213]
	v_lshl_add_u64 v[200:201], v[200:201], 0, v[212:213]
	global_load_dwordx4 v[184:187], v[184:185], off
	global_load_dwordx4 v[200:203], v[200:201], off
	v_or_b32_e32 v190, 48, v229
	v_max_i32_e32 v190, 0, v190
	v_min_i32_e32 v190, s69, v190
	v_lshlrev_b32_e32 v190, s64, v190
	v_add_u32_e32 v190, s65, v190
	v_mad_i64_i32 v[204:205], s[40:41], v190, s33, v[34:35]
	v_lshl_add_u64 v[188:189], v[204:205], 0, s[44:45]
	v_lshl_add_u64 v[204:205], v[204:205], 0, s[46:47]
	v_lshl_add_u64 v[188:189], v[188:189], 0, v[212:213]
	v_lshl_add_u64 v[204:205], v[204:205], 0, v[212:213]
	global_load_dwordx4 v[188:191], v[188:189], off
	global_load_dwordx4 v[204:207], v[204:205], off
	s_waitcnt vmcnt(8)
; #define LAS __attribute__((address_space(3)))
; #define SBAR() __builtin_amdgcn_sched_barrier(0)
; template <int DQK, int DV, int MODE>
; __device__ __forceinline__ void attn_item(LAS unsigned char* lds, int item, const AttnCtx& cx) {
;     ...
;     auto lstore = [&](int b) {
;         LAS unsigned char* base = lds + b * SB;
; #pragma unroll
;         for (int i = 0; i < NKP; ++i) { const int pid = th + 256 * i, row = pid / KPR, cp = pid % KPR; *(LAS u32x4*)(base + koff + row * KP + cp * 16) = kreg[DMA ? 0 : i]; }
;         if (loadV) {
; #pragma unroll
;             for (int i = 0; i < NVP; ++i) { const int pid = th + 256 * i, row = pid / VPR, cp = pid % VPR; *(LAS u32x4*)(base + voff + row * VP + cp * 16) = vreg[DMA ? 0 : i]; }
;         }
;     };
;     ...
;     auto do_qk = [&](int j, bool vpre) {
;         const unsigned kaddr = (unsigned)(size_t)(lds + (j % NST) * SB + koff) + r * KP + 16 * h;
;         const unsigned va = vaddr_of(j);
;         bf16x8 kfr[1][4];
;         K_ISSUE(0, 0);
; #pragma unroll
;         for (int kb = 0; kb < NQF / 2; ++kb) {
;             LGKM0(); SBAR();
;             if (kb == 0) { if (MODE == 1) { s0 = MFMA32(kfr[0][0], qf[0], cin0); s1 = MFMA32(kfr[0][1], qf[0], cin1); } else { s0 = MFMA32(kfr[0][0], qf[0], negm); s1 = MFMA32(kfr[0][1], qf[0], negm); } }
;             else { s0 = MFMA32(kfr[0][0], qf[2 * kb], s0); s1 = MFMA32(kfr[0][1], qf[2 * kb], s1); }
;             s0 = MFMA32(kfr[0][2], qf[2 * kb + 1], s0); s1 = MFMA32(kfr[0][3], qf[2 * kb + 1], s1);
;             SBAR();
;             if (kb + 1 < NQF / 2) K_ISSUE(0, kb + 1); else if (vpre) V_ISSUE(va, 0, 0);
;         }
;     };
;     auto do_soft = [&](int j) {
;         if (MODE == 1) {
;             const int rk = na_rs0 + j; const int bbase = (rk - na_rq + 7) * 31 + 15 - na_cq + 64;
; #pragma unroll
;             for (int i = 0; i < 16; ++i) { s0[i] += biasL[bbase + crow(i, h)]; s1[i] += biasL[bbase + crow(i, h) + 32]; }
;         }
;         if (MODE == 2) {
;             const int lk0 = c_l0 - 64 + 64 * j;
; #pragma unroll
;             for (int i = 0; i < 16; ++i) {
;                 const int lka = lk0 + crow(i, h), lkb = lka + 32;
;                 const bool v0 = (lka >= 0) && (lka < c_L) && (abs(lka - c_lq) <= 64), v1 = (lkb >= 0) && (lkb < c_L) && (abs(lkb - c_lq) <= 64);
;                 s0[i] = v0 ? s0[i] : NEGBIG; s1[i] = v1 ? s1[i] : NEGBIG;
;             }
	ds_write_b128 v36, v[2:5]
	v_mov_b32_e32 v2, 0x1100
	s_movk_i32 s4, 0x110
	v_mad_u32_u24 v231, v41, s4, v2
	v_add3_u32 v2, s70, v231, v212
	ds_write_b128 v2, v[6:9]
	v_mov_b32_e32 v2, 0x2200
	v_mad_u32_u24 v232, v41, s4, v2
	v_add3_u32 v2, s70, v232, v212
	ds_write_b128 v2, v[10:13]
	v_mov_b32_e32 v2, 0x3300
	v_mad_u32_u24 v233, v41, s4, v2
	v_add3_u32 v2, s70, v233, v212
	v_mul_u32_u24_e32 v234, 0x140, v41
	ds_write_b128 v2, v[22:25]
	v_add3_u32 v2, s70, v234, v212
	ds_write_b128 v2, v[30:33] offset:17408
	v_mov_b32_e32 v2, 0x1400
	s_movk_i32 s3, 0x140
	v_mad_u32_u24 v235, v41, s3, v2
	v_add3_u32 v2, s70, v235, v212
	ds_write_b128 v2, v[26:29] offset:17408
	v_mov_b32_e32 v2, 0x2800
	v_mad_u32_u24 v236, v41, s3, v2
	v_add3_u32 v2, s70, v236, v212
	ds_write_b128 v2, v[18:21] offset:17408
	v_mov_b32_e32 v2, 0x3c00
	v_mad_u32_u24 v237, v41, s3, v2
	v_add3_u32 v2, s70, v237, v212
	ds_write_b128 v2, v[14:17] offset:17408
	v_lshrrev_b32_e32 v2, 2, v116
	v_lshlrev_b32_e32 v118, 2, v40
	v_and_or_b32 v2, v2, 3, v118
	v_lshlrev_b32_e32 v215, 3, v116
	v_lshlrev_b32_e32 v4, 1, v116
	v_mul_u32_u24_e32 v2, 0x140, v2
	v_and_b32_e32 v3, 24, v215
	v_and_b32_e32 v4, 32, v4
	v_or3_b32 v239, v3, v4, v2
	s_waitcnt lgkmcnt(0)
	s_barrier
	s_cmp_gt_u32 s1, 1
	s_cselect_b64 s[24:25], -1, 0
	v_mad_u32_u24 v238, v228, s4, v214
	s_mov_b32 s71, 0
	s_and_b64 vcc, exec, s[24:25]
	s_cbranch_vccnz .LBB0_297
	s_cmpk_lt_i32 s0, 0xffc1
	s_cselect_b64 s[38:39], -1, 0
	s_cmp_ge_i32 s0, s68
	s_cselect_b64 s[40:41], -1, 0
	s_or_b64 s[38:39], s[38:39], s[40:41]
	s_and_b64 vcc, exec, s[38:39]
	s_cbranch_vccnz .LBB0_298
	v_add_u32_e32 v50, s70, v238
	ds_read_b128 v[2:5], v50 offset:0
	ds_read_b128 v[6:9], v50 offset:8704
	ds_read_b128 v[34:37], v50 offset:32
	ds_read_b128 v[38:41], v50 offset:8736
	s_waitcnt lgkmcnt(0)
	s_add_i32 s1, s70, 0x4400
	v_add_u32_e32 v119, s1, v239
	v_mfma_f32_32x32x16_bf16 v[18:33], v[2:5], v[144:147], 0
	v_mfma_f32_32x32x16_bf16 v[2:17], v[6:9], v[144:147], 0
	v_mfma_f32_32x32x16_bf16 v[18:33], v[34:37], v[148:151], v[18:33]
	v_mfma_f32_32x32x16_bf16 v[2:17], v[38:41], v[148:151], v[2:17]
	ds_read_b128 v[34:37], v50 offset:64
	ds_read_b128 v[38:41], v50 offset:8768
	ds_read_b128 v[42:45], v50 offset:96
	ds_read_b128 v[46:49], v50 offset:8800
	s_waitcnt lgkmcnt(0)
	s_nop 0
	v_mfma_f32_32x32x16_bf16 v[18:33], v[34:37], v[152:155], v[18:33]
	v_mfma_f32_32x32x16_bf16 v[2:17], v[38:41], v[152:155], v[2:17]
	v_mfma_f32_32x32x16_bf16 v[18:33], v[42:45], v[156:159], v[18:33]
	v_mfma_f32_32x32x16_bf16 v[2:17], v[46:49], v[156:159], v[2:17]
	ds_read_b128 v[34:37], v50 offset:128
	ds_read_b128 v[38:41], v50 offset:8832
	ds_read_b128 v[42:45], v50 offset:160
	ds_read_b128 v[46:49], v50 offset:8864
	s_waitcnt lgkmcnt(0)
	s_nop 0
	v_mfma_f32_32x32x16_bf16 v[18:33], v[34:37], v[160:163], v[18:33]
	v_mfma_f32_32x32x16_bf16 v[2:17], v[38:41], v[160:163], v[2:17]
	v_mfma_f32_32x32x16_bf16 v[18:33], v[42:45], v[164:167], v[18:33]
	v_mfma_f32_32x32x16_bf16 v[2:17], v[46:49], v[164:167], v[2:17]
	ds_read_b128 v[34:37], v50 offset:192
	ds_read_b128 v[38:41], v50 offset:8896
	ds_read_b128 v[42:45], v50 offset:224
	ds_read_b128 v[46:49], v50 offset:8928
	s_waitcnt lgkmcnt(0)
	s_nop 0
	v_mfma_f32_32x32x16_bf16 v[18:33], v[34:37], v[168:171], v[18:33]
	v_mfma_f32_32x32x16_bf16 v[2:17], v[38:41], v[168:171], v[2:17]
	v_mfma_f32_32x32x16_bf16 v[18:33], v[42:45], v[172:175], v[18:33]
	v_mfma_f32_32x32x16_bf16 v[2:17], v[46:49], v[172:175], v[2:17]
	v_or_b32_e32 v50, s0, v118
	v_sub_u32_e32 v52, v50, v0
	s_cmp_gt_i32 s0, -1
	v_sub_u32_e32 v53, 0, v52
	s_cselect_b64 s[54:55], -1, 0
	v_cmp_gt_i32_e32 vcc, s68, v50
	v_max_i32_e32 v52, v52, v53
	v_or_b32_e32 v51, 32, v50
	v_cmp_gt_u32_e64 s[0:1], s20, v52
	s_and_b64 s[38:39], s[54:55], vcc
	s_and_b64 vcc, s[38:39], s[0:1]
	v_cmp_gt_i32_e64 s[38:39], s68, v51
	v_sub_u32_e32 v51, v51, v0
	v_sub_u32_e32 v52, 0, v51
	v_max_i32_e32 v51, v51, v52
	v_or_b32_e32 v52, 1, v50
	v_cmp_lt_i32_e64 s[0:1], s21, v50
	v_cndmask_b32_e32 v18, v220, v18, vcc
	v_cmp_gt_i32_e32 vcc, s68, v52
	v_sub_u32_e32 v52, v52, v0
	v_cmp_gt_u32_e64 s[40:41], s20, v51
	s_and_b64 s[0:1], s[0:1], s[38:39]
	v_sub_u32_e32 v53, 0, v52
	s_and_b64 s[0:1], s[0:1], s[40:41]
	v_max_i32_e32 v52, v52, v53
	v_cndmask_b32_e64 v2, v220, v2, s[0:1]
	v_or_b32_e32 v51, 33, v50
	v_cmp_gt_u32_e64 s[0:1], s20, v52
	s_and_b64 s[38:39], s[54:55], vcc
	s_and_b64 vcc, s[38:39], s[0:1]
	v_cmp_gt_i32_e64 s[38:39], s68, v51
	v_sub_u32_e32 v51, v51, v0
	v_sub_u32_e32 v52, 0, v51
	v_max_i32_e32 v51, v51, v52
	s_movk_i32 s0, 0xffde
	v_cmp_gt_u32_e64 s[40:41], s20, v51
	v_or_b32_e32 v51, 2, v50
	v_cmp_lt_i32_e64 s[0:1], s0, v50
	v_sub_u32_e32 v53, v51, v0
	s_and_b64 s[0:1], s[0:1], s[38:39]
	v_sub_u32_e32 v54, 0, v53
	s_and_b64 s[0:1], s[0:1], s[40:41]
	v_cndmask_b32_e32 v19, v220, v19, vcc
	v_cmp_gt_i32_e32 vcc, s68, v51
	v_max_i32_e32 v53, v53, v54
	v_cndmask_b32_e64 v3, v220, v3, s[0:1]
	v_or_b32_e32 v52, 34, v50
	v_cmp_gt_u32_e64 s[0:1], s20, v53
	s_and_b64 s[38:39], s[54:55], vcc
	s_and_b64 vcc, s[38:39], s[0:1]
	v_cmp_lt_i32_e64 s[0:1], s21, v51
	v_sub_u32_e32 v51, v52, v0
	v_cmp_gt_i32_e64 s[38:39], s68, v52
	v_sub_u32_e32 v52, 0, v51
	v_max_i32_e32 v51, v51, v52
	v_cmp_gt_u32_e64 s[40:41], s20, v51
	v_or_b32_e32 v51, 3, v50
	v_sub_u32_e32 v53, v51, v0
	s_and_b64 s[0:1], s[0:1], s[38:39]
	v_sub_u32_e32 v54, 0, v53
	s_and_b64 s[0:1], s[0:1], s[40:41]
	v_cndmask_b32_e32 v20, v220, v20, vcc
	v_cmp_gt_i32_e32 vcc, s68, v51
	v_max_i32_e32 v53, v53, v54
	v_cndmask_b32_e64 v4, v220, v4, s[0:1]
	v_or_b32_e32 v52, 35, v50
	v_cmp_gt_u32_e64 s[0:1], s20, v53
	s_and_b64 s[38:39], s[54:55], vcc
; __device__ __forceinline__ int crow(int i, int h) { return (i & 3) + 8 * (i >> 2) + 4 * h; }
; template <int DQK, int DV, int MODE>
; __device__ __forceinline__ void attn_item(LAS unsigned char* lds, int item, const AttnCtx& cx) {
;     ...
;         if (MODE == 2) {
;             const int lk0 = c_l0 - 64 + 64 * j;
; #pragma unroll
;             for (int i = 0; i < 16; ++i) {
;                 const int lka = lk0 + crow(i, h), lkb = lka + 32;
;                 const bool v0 = (lka >= 0) && (lka < c_L) && (abs(lka - c_lq) <= 64), v1 = (lkb >= 0) && (lkb < c_L) && (abs(lkb - c_lq) <= 64);
;                 s0[i] = v0 ? s0[i] : NEGBIG; s1[i] = v1 ? s1[i] : NEGBIG;
;             }
	s_and_b64 vcc, s[38:39], s[0:1]
	v_cmp_lt_i32_e64 s[0:1], s21, v51
	v_sub_u32_e32 v51, v52, v0
	v_cmp_gt_i32_e64 s[38:39], s68, v52
	v_sub_u32_e32 v52, 0, v51
	v_max_i32_e32 v51, v51, v52
	v_cmp_gt_u32_e64 s[40:41], s20, v51
	v_or_b32_e32 v51, 8, v50
	v_sub_u32_e32 v53, v51, v0
	s_and_b64 s[0:1], s[0:1], s[38:39]
	v_sub_u32_e32 v54, 0, v53
	s_and_b64 s[0:1], s[0:1], s[40:41]
	v_cndmask_b32_e32 v21, v220, v21, vcc
	v_cmp_gt_i32_e32 vcc, s68, v51
	v_max_i32_e32 v53, v53, v54
	v_cndmask_b32_e64 v5, v220, v5, s[0:1]
	v_or_b32_e32 v52, 40, v50
	v_cmp_gt_u32_e64 s[0:1], s20, v53
	s_and_b64 s[38:39], s[54:55], vcc
	s_and_b64 vcc, s[38:39], s[0:1]
	v_cmp_lt_i32_e64 s[0:1], s21, v51
	v_sub_u32_e32 v51, v52, v0
	v_cmp_gt_i32_e64 s[38:39], s68, v52
	v_sub_u32_e32 v52, 0, v51
	v_max_i32_e32 v51, v51, v52
	v_cmp_gt_u32_e64 s[40:41], s20, v51
	v_or_b32_e32 v51, 9, v50
	v_sub_u32_e32 v53, v51, v0
	s_and_b64 s[0:1], s[0:1], s[38:39]
	v_sub_u32_e32 v54, 0, v53
	s_and_b64 s[0:1], s[0:1], s[40:41]
	v_cndmask_b32_e32 v22, v220, v22, vcc
	v_cmp_gt_i32_e32 vcc, s68, v51
	v_max_i32_e32 v53, v53, v54
	v_cndmask_b32_e64 v6, v220, v6, s[0:1]
	v_or_b32_e32 v52, 41, v50
	v_cmp_gt_u32_e64 s[0:1], s20, v53
	s_and_b64 s[38:39], s[54:55], vcc
	s_and_b64 vcc, s[38:39], s[0:1]
	v_cmp_lt_i32_e64 s[0:1], s21, v51
	v_sub_u32_e32 v51, v52, v0
	v_cmp_gt_i32_e64 s[38:39], s68, v52
	v_sub_u32_e32 v52, 0, v51
	v_max_i32_e32 v51, v51, v52
	v_cmp_gt_u32_e64 s[40:41], s20, v51
	v_or_b32_e32 v51, 10, v50
	v_sub_u32_e32 v53, v51, v0
	s_and_b64 s[0:1], s[0:1], s[38:39]
	v_sub_u32_e32 v54, 0, v53
	s_and_b64 s[0:1], s[0:1], s[40:41]
	v_cndmask_b32_e32 v23, v220, v23, vcc
	v_cmp_gt_i32_e32 vcc, s68, v51
	v_max_i32_e32 v53, v53, v54
	v_cndmask_b32_e64 v7, v220, v7, s[0:1]
	v_or_b32_e32 v52, 42, v50
	v_cmp_gt_u32_e64 s[0:1], s20, v53
	s_and_b64 s[38:39], s[54:55], vcc
	s_and_b64 vcc, s[38:39], s[0:1]
	v_cmp_lt_i32_e64 s[0:1], s21, v51
	v_sub_u32_e32 v51, v52, v0
	v_cmp_gt_i32_e64 s[38:39], s68, v52
	v_sub_u32_e32 v52, 0, v51
	v_max_i32_e32 v51, v51, v52
	v_cmp_gt_u32_e64 s[40:41], s20, v51
	v_or_b32_e32 v51, 11, v50
	v_sub_u32_e32 v53, v51, v0
	s_and_b64 s[0:1], s[0:1], s[38:39]
	v_sub_u32_e32 v54, 0, v53
	s_and_b64 s[0:1], s[0:1], s[40:41]
	v_cndmask_b32_e32 v24, v220, v24, vcc
	v_cmp_gt_i32_e32 vcc, s68, v51
	v_max_i32_e32 v53, v53, v54
	v_cndmask_b32_e64 v8, v220, v8, s[0:1]
	v_or_b32_e32 v52, 43, v50
	v_cmp_gt_u32_e64 s[0:1], s20, v53
	s_and_b64 s[38:39], s[54:55], vcc
	s_and_b64 vcc, s[38:39], s[0:1]
	v_cmp_lt_i32_e64 s[0:1], s21, v51
	v_sub_u32_e32 v51, v52, v0
	v_cmp_gt_i32_e64 s[38:39], s68, v52
	v_sub_u32_e32 v52, 0, v51
	v_max_i32_e32 v51, v51, v52
	v_cmp_gt_u32_e64 s[40:41], s20, v51
	v_or_b32_e32 v51, 16, v50
	v_sub_u32_e32 v53, v51, v0
	s_and_b64 s[0:1], s[0:1], s[38:39]
	v_sub_u32_e32 v54, 0, v53
	s_and_b64 s[0:1], s[0:1], s[40:41]
	v_cndmask_b32_e32 v25, v220, v25, vcc
	v_cmp_gt_i32_e32 vcc, s68, v51
	v_max_i32_e32 v53, v53, v54
	v_cndmask_b32_e64 v9, v220, v9, s[0:1]
	v_or_b32_e32 v52, 48, v50
	v_cmp_gt_u32_e64 s[0:1], s20, v53
	s_and_b64 s[38:39], s[54:55], vcc
	s_and_b64 vcc, s[38:39], s[0:1]
	v_cmp_lt_i32_e64 s[0:1], s21, v51
	v_sub_u32_e32 v51, v52, v0
	v_cmp_gt_i32_e64 s[38:39], s68, v52
	v_sub_u32_e32 v52, 0, v51
	v_max_i32_e32 v51, v51, v52
	v_cmp_gt_u32_e64 s[40:41], s20, v51
	v_or_b32_e32 v51, 17, v50
	v_sub_u32_e32 v53, v51, v0
	s_and_b64 s[0:1], s[0:1], s[38:39]
	v_sub_u32_e32 v54, 0, v53
	s_and_b64 s[0:1], s[0:1], s[40:41]
	v_cndmask_b32_e32 v26, v220, v26, vcc
	v_cmp_gt_i32_e32 vcc, s68, v51
	v_max_i32_e32 v53, v53, v54
	v_cndmask_b32_e64 v10, v220, v10, s[0:1]
	v_or_b32_e32 v52, 49, v50
	v_cmp_gt_u32_e64 s[0:1], s20, v53
	s_and_b64 s[38:39], s[54:55], vcc
	s_and_b64 vcc, s[38:39], s[0:1]
	v_cmp_lt_i32_e64 s[0:1], s21, v51
	v_sub_u32_e32 v51, v52, v0
	v_cmp_gt_i32_e64 s[38:39], s68, v52
	v_sub_u32_e32 v52, 0, v51
	v_max_i32_e32 v51, v51, v52
	v_cmp_gt_u32_e64 s[40:41], s20, v51
	v_or_b32_e32 v51, 18, v50
	v_sub_u32_e32 v53, v51, v0
	s_and_b64 s[0:1], s[0:1], s[38:39]
	v_sub_u32_e32 v54, 0, v53
	s_and_b64 s[0:1], s[0:1], s[40:41]
	v_cndmask_b32_e32 v27, v220, v27, vcc
	v_cmp_gt_i32_e32 vcc, s68, v51
	v_max_i32_e32 v53, v53, v54
	v_cndmask_b32_e64 v11, v220, v11, s[0:1]
	v_or_b32_e32 v52, 50, v50
	v_cmp_gt_u32_e64 s[0:1], s20, v53
	s_and_b64 s[38:39], s[54:55], vcc
	s_and_b64 vcc, s[38:39], s[0:1]
	v_cmp_lt_i32_e64 s[0:1], s21, v51
	v_sub_u32_e32 v51, v52, v0
	v_cmp_gt_i32_e64 s[38:39], s68, v52
	v_sub_u32_e32 v52, 0, v51
	v_max_i32_e32 v51, v51, v52
	v_cmp_gt_u32_e64 s[40:41], s20, v51
	v_or_b32_e32 v51, 19, v50
	v_sub_u32_e32 v53, v51, v0
	s_and_b64 s[0:1], s[0:1], s[38:39]
	v_sub_u32_e32 v54, 0, v53
	s_and_b64 s[0:1], s[0:1], s[40:41]
	v_cndmask_b32_e32 v28, v220, v28, vcc
	v_cmp_gt_i32_e32 vcc, s68, v51
	v_max_i32_e32 v53, v53, v54
	v_cndmask_b32_e64 v12, v220, v12, s[0:1]
	v_or_b32_e32 v52, 51, v50
	v_cmp_gt_u32_e64 s[0:1], s20, v53
	s_and_b64 s[38:39], s[54:55], vcc
	s_and_b64 vcc, s[38:39], s[0:1]
	v_cmp_lt_i32_e64 s[0:1], s21, v51
	v_sub_u32_e32 v51, v52, v0
	v_cmp_gt_i32_e64 s[38:39], s68, v52
	v_sub_u32_e32 v52, 0, v51
	v_max_i32_e32 v51, v51, v52
	v_cmp_gt_u32_e64 s[40:41], s20, v51
	v_or_b32_e32 v51, 24, v50
	v_sub_u32_e32 v53, v51, v0
	s_and_b64 s[0:1], s[0:1], s[38:39]
	v_sub_u32_e32 v54, 0, v53
	s_and_b64 s[0:1], s[0:1], s[40:41]
	v_cndmask_b32_e32 v29, v220, v29, vcc
	v_cmp_gt_i32_e32 vcc, s68, v51
	v_max_i32_e32 v53, v53, v54
	v_cndmask_b32_e64 v13, v220, v13, s[0:1]
	v_or_b32_e32 v52, 56, v50
	v_cmp_gt_u32_e64 s[0:1], s20, v53
	s_and_b64 s[38:39], s[54:55], vcc
	s_and_b64 vcc, s[38:39], s[0:1]
	v_cmp_lt_i32_e64 s[0:1], s21, v51
; __device__ __forceinline__ int crow(int i, int h) { return (i & 3) + 8 * (i >> 2) + 4 * h; }
; __device__ __forceinline__ float max3f(float a, float b, float c) { float r; asm("v_max3_f32 %0, %1, %2, %3" : "=v"(r) : "v"(a), "v"(b), "v"(c)); return r; }
; template <int DQK, int DV, int MODE>
; __device__ __forceinline__ void attn_item(LAS unsigned char* lds, int item, const AttnCtx& cx) {
;     ...
;             for (int i = 0; i < 16; ++i) {
;                 const int lka = lk0 + crow(i, h), lkb = lka + 32;
;                 const bool v0 = (lka >= 0) && (lka < c_L) && (abs(lka - c_lq) <= 64), v1 = (lkb >= 0) && (lkb < c_L) && (abs(lkb - c_lq) <= 64);
;                 s0[i] = v0 ? s0[i] : NEGBIG; s1[i] = v1 ? s1[i] : NEGBIG;
;             }
;         }
;         float mx = max3f(s0[0], s1[0], s0[1]);
;         mx = max3f(mx, s1[1], s0[2]);
; #pragma unroll
;         for (int i = 2; i < 15; ++i) mx = max3f(mx, s1[i], s0[i + 1]);
;         mx = fmaxf(mx, s1[15]);
;         { auto rr = __builtin_amdgcn_permlane32_swap(__float_as_uint(mx), __float_as_uint(mx), false, false); mx = max3f(__uint_as_float(rr[0]), __uint_as_float(rr[1]), __uint_as_float(rr[0])); }
	v_sub_u32_e32 v51, v52, v0
	v_cmp_gt_i32_e64 s[38:39], s68, v52
	v_sub_u32_e32 v52, 0, v51
	v_max_i32_e32 v51, v51, v52
	v_cmp_gt_u32_e64 s[40:41], s20, v51
	v_or_b32_e32 v51, 25, v50
	v_sub_u32_e32 v53, v51, v0
	s_and_b64 s[0:1], s[0:1], s[38:39]
	v_sub_u32_e32 v54, 0, v53
	s_and_b64 s[0:1], s[0:1], s[40:41]
	v_cndmask_b32_e32 v30, v220, v30, vcc
	v_cmp_gt_i32_e32 vcc, s68, v51
	v_max_i32_e32 v53, v53, v54
	v_cndmask_b32_e64 v14, v220, v14, s[0:1]
	v_or_b32_e32 v52, 57, v50
	v_cmp_gt_u32_e64 s[0:1], s20, v53
	s_and_b64 s[38:39], s[54:55], vcc
	s_and_b64 vcc, s[38:39], s[0:1]
	v_cmp_lt_i32_e64 s[0:1], s21, v51
	v_sub_u32_e32 v51, v52, v0
	v_cmp_gt_i32_e64 s[38:39], s68, v52
	v_sub_u32_e32 v52, 0, v51
	v_max_i32_e32 v51, v51, v52
	v_cmp_gt_u32_e64 s[40:41], s20, v51
	v_or_b32_e32 v51, 26, v50
	v_sub_u32_e32 v53, v51, v0
	s_and_b64 s[0:1], s[0:1], s[38:39]
	v_sub_u32_e32 v54, 0, v53
	s_and_b64 s[0:1], s[0:1], s[40:41]
	v_cndmask_b32_e32 v31, v220, v31, vcc
	v_cmp_gt_i32_e32 vcc, s68, v51
	v_max_i32_e32 v53, v53, v54
	v_cndmask_b32_e64 v15, v220, v15, s[0:1]
	v_or_b32_e32 v52, 58, v50
	v_cmp_gt_u32_e64 s[0:1], s20, v53
	s_and_b64 s[38:39], s[54:55], vcc
	s_and_b64 vcc, s[38:39], s[0:1]
	v_cmp_lt_i32_e64 s[0:1], s21, v51
	v_sub_u32_e32 v51, v52, v0
	v_cmp_gt_i32_e64 s[38:39], s68, v52
	v_sub_u32_e32 v52, 0, v51
	v_max_i32_e32 v51, v51, v52
	v_cmp_gt_u32_e64 s[40:41], s20, v51
	v_or_b32_e32 v51, 27, v50
	v_sub_u32_e32 v52, v51, v0
	s_and_b64 s[0:1], s[0:1], s[38:39]
	v_sub_u32_e32 v53, 0, v52
	s_and_b64 s[0:1], s[0:1], s[40:41]
	v_cndmask_b32_e32 v32, v220, v32, vcc
	v_or_b32_e32 v50, 59, v50
	v_cmp_gt_i32_e32 vcc, s68, v51
	v_max_i32_e32 v52, v52, v53
	v_cndmask_b32_e64 v16, v220, v16, s[0:1]
	v_cmp_gt_u32_e64 s[0:1], s20, v52
	s_and_b64 s[38:39], s[54:55], vcc
	v_sub_u32_e32 v0, v50, v0
	s_and_b64 vcc, s[38:39], s[0:1]
	v_cmp_gt_i32_e64 s[38:39], s68, v50
	v_sub_u32_e32 v50, 0, v0
	v_max_i32_e32 v0, v0, v50
	v_cmp_gt_u32_e64 s[40:41], s20, v0
	v_cndmask_b32_e32 v0, v220, v33, vcc
	v_max3_f32 v33, v18, v2, v19
	v_cmp_lt_i32_e64 s[0:1], s21, v51
	v_max3_f32 v33, v33, v3, v20
	s_and_b64 s[0:1], s[0:1], s[38:39]
	v_max3_f32 v33, v33, v4, v21
	s_and_b64 s[0:1], s[0:1], s[40:41]
	v_max3_f32 v33, v33, v5, v22
	v_cndmask_b32_e64 v17, v220, v17, s[0:1]
	v_max3_f32 v33, v33, v6, v23
	v_max_f32_e32 v50, v17, v17
	v_max3_f32 v33, v33, v7, v24
	s_mov_b32 s89, s88
	v_max3_f32 v33, v33, v8, v25
	s_mov_b32 s90, s88
	v_max3_f32 v33, v33, v9, v26
	s_mov_b32 s91, s88
	v_max3_f32 v33, v33, v10, v27
	ds_read_b64_tr_b16 v[46:47], v119 offset:0
	ds_read_b64_tr_b16 v[48:49], v119 offset:2560
	ds_read_b64_tr_b16 v[42:43], v119 offset:5120
	ds_read_b64_tr_b16 v[44:45], v119 offset:7680
	ds_read_b64_tr_b16 v[38:39], v119 offset:10240
	s_nop 0
	v_max3_f32 v33, v33, v11, v28
	ds_read_b64_tr_b16 v[40:41], v119 offset:12800
	ds_read_b64_tr_b16 v[34:35], v119 offset:15360
	ds_read_b64_tr_b16 v[36:37], v119 offset:17920
	s_waitcnt lgkmcnt(0)
; #define LGKM0() asm volatile("s_waitcnt lgkmcnt(0)" ::: "memory")
; template <int DQK, int DV, int MODE>
; __device__ __forceinline__ void attn_item(LAS unsigned char* lds, int item, const AttnCtx& cx) {
;     ...
;         float mx = max3f(s0[0], s1[0], s0[1]);
;         mx = max3f(mx, s1[1], s0[2]);
; #pragma unroll
;         for (int i = 2; i < 15; ++i) mx = max3f(mx, s1[i], s0[i + 1]);
;         mx = fmaxf(mx, s1[15]);
;         { auto rr = __builtin_amdgcn_permlane32_swap(__float_as_uint(mx), __float_as_uint(mx), false, false); mx = max3f(__uint_as_float(rr[0]), __uint_as_float(rr[1]), __uint_as_float(rr[0])); }
;         if (first || __builtin_amdgcn_ballot_w64(mx > THR) != 0ull) {
;             const float delta = first ? mx : fmaxf(mx, 0.f), alpha = fast_exp2(-delta);
; #pragma unroll
;             for (int i = 0; i < 16; ++i) { s0[i] -= delta; s1[i] -= delta; }
;             if (!first) {
; #pragma unroll
;                 for (int d = 0; d < NDV; ++d)
; #pragma unroll
;                     for (int i = 0; i < 16; ++i) O[d][i] *= alpha;
; #pragma unroll
;                 for (int i = 0; i < 16; ++i) Lacc[i] *= alpha;
;             }
;             mhat += delta;
; #pragma unroll
;             for (int i = 0; i < 16; ++i) negm[i] = -mhat;
;             if (MODE == 1) set_cin();
;             first = false;
;         }
; #pragma unroll
;         for (int i = 0; i < 16; ++i) { s0[i] = fast_exp2(s0[i]); s1[i] = fast_exp2(s1[i]); }
;         u32x4 w;
;         w.x = pk2(s0[0], s0[1]); w.y = pk2(s0[2], s0[3]); w.z = pk2(s0[4], s0[5]); w.w = pk2(s0[6], s0[7]); pa[0][0] = __builtin_bit_cast(bf16x8, w);
;         w.x = pk2(s0[8], s0[9]); w.y = pk2(s0[10], s0[11]); w.z = pk2(s0[12], s0[13]); w.w = pk2(s0[14], s0[15]); pa[0][1] = __builtin_bit_cast(bf16x8, w);
;         w.x = pk2(s1[0], s1[1]); w.y = pk2(s1[2], s1[3]); w.z = pk2(s1[4], s1[5]); w.w = pk2(s1[6], s1[7]); pa[1][0] = __builtin_bit_cast(bf16x8, w);
;         w.x = pk2(s1[8], s1[9]); w.y = pk2(s1[10], s1[11]); w.z = pk2(s1[12], s1[13]); w.w = pk2(s1[14], s1[15]); pa[1][1] = __builtin_bit_cast(bf16x8, w);
;     };
;     auto do_pv = [&](unsigned va) {
; #pragma unroll
;         for (int k4 = 0; k4 < 4; ++k4) Lacc = MFMA32(ones8, pa[k4 >> 1][k4 & 1], Lacc);
; #pragma unroll
;         for (int d = 0; d < NDV; ++d) {
;             LGKM0(); SBAR();
; #pragma unroll
;             for (int k4 = 0; k4 < 4; ++k4) {
	s_nop 0
	v_max3_f32 v33, v33, v12, v29
	s_nop 0
	v_max3_f32 v33, v33, v13, v30
	s_nop 0
	v_max3_f32 v33, v33, v14, v31
	s_nop 0
	v_max3_f32 v33, v33, v15, v32
	s_nop 0
	v_max3_f32 v33, v33, v16, v0
	s_nop 0
	v_max_f32_e32 v33, v33, v33
	v_max_f32_e32 v33, v33, v50
	v_mov_b32_e32 v50, v33
	s_nop 1
	v_permlane32_swap_b32_e32 v33, v50
	v_max3_f32 v33, v33, v50, v33
	v_mov_b64_e32 v[50:51], s[88:89]
	v_sub_f32_e32 v18, v18, v33
	v_sub_f32_e32 v19, v19, v33
	v_sub_f32_e32 v20, v20, v33
	v_sub_f32_e32 v21, v21, v33
	v_sub_f32_e32 v22, v22, v33
	v_sub_f32_e32 v6, v6, v33
	v_sub_f32_e32 v23, v23, v33
	v_sub_f32_e32 v7, v7, v33
	v_sub_f32_e32 v24, v24, v33
	v_sub_f32_e32 v8, v8, v33
	v_sub_f32_e32 v25, v25, v33
	v_sub_f32_e32 v2, v2, v33
	v_sub_f32_e32 v3, v3, v33
	v_sub_f32_e32 v4, v4, v33
	v_sub_f32_e32 v5, v5, v33
	v_sub_f32_e32 v9, v9, v33
	v_sub_f32_e32 v26, v26, v33
	v_sub_f32_e32 v10, v10, v33
	v_sub_f32_e32 v27, v27, v33
	v_sub_f32_e32 v11, v11, v33
	v_sub_f32_e32 v28, v28, v33
	v_sub_f32_e32 v12, v12, v33
	v_sub_f32_e32 v29, v29, v33
	v_sub_f32_e32 v13, v13, v33
	v_sub_f32_e32 v30, v30, v33
	v_sub_f32_e32 v14, v14, v33
	v_sub_f32_e32 v31, v31, v33
	v_sub_f32_e32 v15, v15, v33
	v_sub_f32_e32 v32, v32, v33
	v_sub_f32_e32 v16, v16, v33
	v_sub_f32_e32 v0, v0, v33
	v_sub_f32_e32 v17, v17, v33
	v_add_f32_e32 v213, 0, v33
	v_exp_f32_e32 v18, v18
	v_exp_f32_e32 v19, v19
	v_exp_f32_e32 v20, v20
	v_exp_f32_e32 v21, v21
	v_exp_f32_e32 v22, v22
	v_exp_f32_e32 v33, v6
	v_exp_f32_e32 v6, v23
	v_exp_f32_e32 v23, v7
	v_exp_f32_e32 v7, v24
	v_exp_f32_e32 v24, v8
	v_exp_f32_e32 v8, v25
	v_mov_b64_e32 v[52:53], s[90:91]
	v_exp_f32_e32 v2, v2
	v_exp_f32_e32 v3, v3
	v_exp_f32_e32 v4, v4
	v_exp_f32_e32 v5, v5
	v_exp_f32_e32 v9, v9
	v_exp_f32_e32 v25, v26
	v_exp_f32_e32 v26, v10
	v_exp_f32_e32 v10, v27
	v_exp_f32_e32 v27, v11
	v_exp_f32_e32 v11, v28
	v_exp_f32_e32 v28, v12
	v_exp_f32_e32 v12, v29
	v_exp_f32_e32 v29, v13
	v_exp_f32_e32 v13, v30
	v_exp_f32_e32 v30, v31
	v_exp_f32_e32 v31, v32
	v_exp_f32_e32 v16, v16
	v_exp_f32_e32 v0, v0
	v_exp_f32_e32 v17, v17
	v_cvt_pk_bf16_f32 v112, v18, v19
	v_cvt_pk_bf16_f32 v113, v20, v21
	v_cvt_pk_bf16_f32 v114, v22, v6
	v_cvt_pk_bf16_f32 v115, v7, v8
	v_cvt_pk_bf16_f32 v10, v25, v10
	v_cvt_pk_bf16_f32 v11, v11, v12
	v_cvt_pk_bf16_f32 v12, v13, v30
	v_cvt_pk_bf16_f32 v13, v31, v0
	v_cvt_pk_bf16_f32 v6, v2, v3
	v_cvt_pk_bf16_f32 v7, v4, v5
	v_cvt_pk_bf16_f32 v8, v33, v23
	v_cvt_pk_bf16_f32 v9, v24, v9
	v_cvt_pk_bf16_f32 v2, v26, v27
	v_cvt_pk_bf16_f32 v3, v28, v29
	v_cvt_pk_bf16_f32 v5, v16, v17
	v_mfma_f32_32x32x16_bf16 v[16:31], v[50:53], v[112:115], 0
	v_exp_f32_e32 v14, v14
	v_exp_f32_e32 v15, v15
	v_xor_b32_e32 v96, 0x80000000, v213
	v_mov_b32_e32 v97, v96
	v_mov_b32_e32 v98, v96
	v_cvt_pk_bf16_f32 v4, v14, v15
	v_mov_b32_e32 v99, v96
	v_mfma_f32_32x32x16_bf16 v[16:31], v[50:53], v[10:13], v[16:31]
	v_mov_b32_e32 v100, v96
	v_mov_b32_e32 v101, v96
	v_mov_b32_e32 v102, v96
	v_mov_b32_e32 v103, v96
	v_mov_b32_e32 v104, v96
	v_mov_b32_e32 v105, v96
	v_mov_b32_e32 v106, v96
	v_mfma_f32_32x32x16_bf16 v[16:31], v[50:53], v[6:9], v[16:31]
	v_mov_b32_e32 v107, v96
	v_mov_b32_e32 v108, v96
	v_mov_b32_e32 v109, v96
	v_mov_b32_e32 v110, v96
	v_mov_b32_e32 v111, v96
	v_mfma_f32_32x32x16_bf16 v[16:31], v[50:53], v[2:5], v[16:31]
	v_mfma_f32_32x32x16_bf16 v[80:95], v[46:49], v[112:115], 0
	v_mfma_f32_32x32x16_bf16 v[80:95], v[42:45], v[10:13], v[80:95]
	v_mfma_f32_32x32x16_bf16 v[80:95], v[38:41], v[6:9], v[80:95]
	v_mfma_f32_32x32x16_bf16 v[80:95], v[34:37], v[2:5], v[80:95]
	ds_read_b64_tr_b16 v[32:33], v119 offset:64
	ds_read_b64_tr_b16 v[34:35], v119 offset:2624
	ds_read_b64_tr_b16 v[36:37], v119 offset:5184
	ds_read_b64_tr_b16 v[38:39], v119 offset:7744
	ds_read_b64_tr_b16 v[40:41], v119 offset:10304
	ds_read_b64_tr_b16 v[42:43], v119 offset:12864
	ds_read_b64_tr_b16 v[44:45], v119 offset:15424
	ds_read_b64_tr_b16 v[46:47], v119 offset:17984
	s_waitcnt lgkmcnt(0)
	s_nop 0
	v_mfma_f32_32x32x16_bf16 v[64:79], v[32:35], v[112:115], 0
	v_mfma_f32_32x32x16_bf16 v[64:79], v[36:39], v[10:13], v[64:79]
	v_mfma_f32_32x32x16_bf16 v[64:79], v[40:43], v[6:9], v[64:79]
	v_mfma_f32_32x32x16_bf16 v[64:79], v[44:47], v[2:5], v[64:79]
	ds_read_b64_tr_b16 v[32:33], v119 offset:128
	ds_read_b64_tr_b16 v[34:35], v119 offset:2688
	ds_read_b64_tr_b16 v[36:37], v119 offset:5248
	ds_read_b64_tr_b16 v[38:39], v119 offset:7808
	ds_read_b64_tr_b16 v[40:41], v119 offset:10368
	ds_read_b64_tr_b16 v[42:43], v119 offset:12928
	ds_read_b64_tr_b16 v[44:45], v119 offset:15488
	ds_read_b64_tr_b16 v[46:47], v119 offset:18048
	s_waitcnt lgkmcnt(0)
	s_nop 0
	v_mfma_f32_32x32x16_bf16 v[48:63], v[32:35], v[112:115], 0
	v_mfma_f32_32x32x16_bf16 v[48:63], v[36:39], v[10:13], v[48:63]
	v_mfma_f32_32x32x16_bf16 v[48:63], v[40:43], v[6:9], v[48:63]
	v_mfma_f32_32x32x16_bf16 v[48:63], v[44:47], v[2:5], v[48:63]
	ds_read_b64_tr_b16 v[32:33], v119 offset:192
	ds_read_b64_tr_b16 v[34:35], v119 offset:2752
	ds_read_b64_tr_b16 v[120:121], v119 offset:5312
	ds_read_b64_tr_b16 v[122:123], v119 offset:7872
	ds_read_b64_tr_b16 v[124:125], v119 offset:10432
	ds_read_b64_tr_b16 v[126:127], v119 offset:12992
	ds_read_b64_tr_b16 v[128:129], v119 offset:15552
	ds_read_b64_tr_b16 v[130:131], v119 offset:18112
	s_waitcnt lgkmcnt(0)
	s_nop 0
	v_mfma_f32_32x32x16_bf16 v[32:47], v[32:35], v[112:115], 0
	v_mfma_f32_32x32x16_bf16 v[32:47], v[120:123], v[10:13], v[32:47]
	v_mfma_f32_32x32x16_bf16 v[32:47], v[124:127], v[6:9], v[32:47]
	v_mfma_f32_32x32x16_bf16 v[32:47], v[128:131], v[2:5], v[32:47]
	s_mov_b64 s[56:57], 0
	s_branch .LBB0_299

; #define MFMA32(a, b, c) __builtin_amdgcn_mfma_f32_32x32x16_bf16((a), (b), (c), 0, 0, 0)
; #define LGKM0() asm volatile("s_waitcnt lgkmcnt(0)" ::: "memory")
; #define SBAR() __builtin_amdgcn_sched_barrier(0)
; #define V_ISSUE(va, b, d) do { _Pragma("unroll") for (int k4 = 0; k4 < 4; ++k4) { DS_TR16(vlo[b][k4], va, (16 * k4) * VP + (d) * 64); DS_TR16(vhi[b][k4], va, (16 * k4 + 8) * VP + (d) * 64); } } while (0)
; #define K_ISSUE(b, kb) do { DS_RD128(kfr[b][0], kaddr, (2 * (kb)) * 32); DS_RD128(kfr[b][1], kaddr, 32 * KP + (2 * (kb)) * 32); \
;                             DS_RD128(kfr[b][2], kaddr, (2 * (kb) + 1) * 32); DS_RD128(kfr[b][3], kaddr, 32 * KP + (2 * (kb) + 1) * 32); } while (0)
; template <int DQK, int DV, int MODE>
; __device__ __forceinline__ void attn_item(LAS unsigned char* lds, int item, const AttnCtx& cx) {
;     ...
;     auto do_qk = [&](int j, bool vpre) {
;         const unsigned kaddr = (unsigned)(size_t)(lds + (j % NST) * SB + koff) + r * KP + 16 * h;
;         const unsigned va = vaddr_of(j);
;         bf16x8 kfr[1][4];
;         K_ISSUE(0, 0);
; #pragma unroll
;         for (int kb = 0; kb < NQF / 2; ++kb) {
;             LGKM0(); SBAR();
;             if (kb == 0) { if (MODE == 1) { s0 = MFMA32(kfr[0][0], qf[0], cin0); s1 = MFMA32(kfr[0][1], qf[0], cin1); } else { s0 = MFMA32(kfr[0][0], qf[0], negm); s1 = MFMA32(kfr[0][1], qf[0], negm); } }
;             else { s0 = MFMA32(kfr[0][0], qf[2 * kb], s0); s1 = MFMA32(kfr[0][1], qf[2 * kb], s1); }
;             s0 = MFMA32(kfr[0][2], qf[2 * kb + 1], s0); s1 = MFMA32(kfr[0][3], qf[2 * kb + 1], s1);
;             SBAR();
;             if (kb + 1 < NQF / 2) K_ISSUE(0, kb + 1); else if (vpre) V_ISSUE(va, 0, 0);
;         }
.LBB0_309:
	s_xor_b64 s[58:59], s[56:57], -1
	s_add_i32 s0, s30, -1
	s_add_i32 s1, s30, -3
	s_cmp_lt_u32 s0, 2
	s_cselect_b32 s0, s0, s1
	s_mul_i32 s0, s0, 0x12800
	s_add_i32 s0, s70, s0
	v_add_u32_e32 v216, s0, v238
	ds_read_b128 v[2:5], v216 offset:0
	ds_read_b128 v[6:9], v216 offset:8704
	ds_read_b128 v[10:13], v216 offset:32
	ds_read_b128 v[208:211], v216 offset:8736
	s_waitcnt lgkmcnt(0)
	s_addk_i32 s0, 0x4400
	v_add_u32_e32 v241, s0, v239
	v_mfma_f32_32x32x16_bf16 v[128:143], v[2:5], v[144:147], v[96:111]
	v_mfma_f32_32x32x16_bf16 v[112:127], v[6:9], v[144:147], v[96:111]
	v_mfma_f32_32x32x16_bf16 v[128:143], v[10:13], v[148:151], v[128:143]
	v_mfma_f32_32x32x16_bf16 v[112:127], v[208:211], v[148:151], v[112:127]
	ds_read_b128 v[2:5], v216 offset:64
	ds_read_b128 v[6:9], v216 offset:8768
	ds_read_b128 v[10:13], v216 offset:96
	ds_read_b128 v[208:211], v216 offset:8800
	s_waitcnt lgkmcnt(0)
	s_nop 0
	v_mfma_f32_32x32x16_bf16 v[128:143], v[2:5], v[152:155], v[128:143]
	v_mfma_f32_32x32x16_bf16 v[112:127], v[6:9], v[152:155], v[112:127]
	v_mfma_f32_32x32x16_bf16 v[128:143], v[10:13], v[156:159], v[128:143]
	v_mfma_f32_32x32x16_bf16 v[112:127], v[208:211], v[156:159], v[112:127]
	ds_read_b128 v[2:5], v216 offset:128
	ds_read_b128 v[6:9], v216 offset:8832
	ds_read_b128 v[10:13], v216 offset:160
	ds_read_b128 v[208:211], v216 offset:8864
	s_waitcnt lgkmcnt(0)
	s_nop 0
	v_mfma_f32_32x32x16_bf16 v[128:143], v[2:5], v[160:163], v[128:143]
	v_mfma_f32_32x32x16_bf16 v[112:127], v[6:9], v[160:163], v[112:127]
	v_mfma_f32_32x32x16_bf16 v[128:143], v[10:13], v[164:167], v[128:143]
	v_mfma_f32_32x32x16_bf16 v[112:127], v[208:211], v[164:167], v[112:127]
	ds_read_b128 v[2:5], v216 offset:192
	ds_read_b128 v[6:9], v216 offset:8896
	ds_read_b128 v[10:13], v216 offset:224
	ds_read_b128 v[208:211], v216 offset:8928
	s_waitcnt lgkmcnt(0)
; __device__ __forceinline__ int crow(int i, int h) { return (i & 3) + 8 * (i >> 2) + 4 * h; }
; __device__ __forceinline__ float max3f(float a, float b, float c) { float r; asm("v_max3_f32 %0, %1, %2, %3" : "=v"(r) : "v"(a), "v"(b), "v"(c)); return r; }
; template <int DQK, int DV, int MODE>
; __device__ __forceinline__ void attn_item(LAS unsigned char* lds, int item, const AttnCtx& cx) {
;     ...
;         if (MODE == 2) {
;             const int lk0 = c_l0 - 64 + 64 * j;
; #pragma unroll
;             for (int i = 0; i < 16; ++i) {
;                 const int lka = lk0 + crow(i, h), lkb = lka + 32;
;                 const bool v0 = (lka >= 0) && (lka < c_L) && (abs(lka - c_lq) <= 64), v1 = (lkb >= 0) && (lkb < c_L) && (abs(lkb - c_lq) <= 64);
;                 s0[i] = v0 ? s0[i] : NEGBIG; s1[i] = v1 ? s1[i] : NEGBIG;
;             }
;         }
;         float mx = max3f(s0[0], s1[0], s0[1]);
;         mx = max3f(mx, s1[1], s0[2]);
; #pragma unroll
;         for (int i = 2; i < 15; ++i) mx = max3f(mx, s1[i], s0[i + 1]);
;         mx = fmaxf(mx, s1[15]);
;         { auto rr = __builtin_amdgcn_permlane32_swap(__float_as_uint(mx), __float_as_uint(mx), false, false); mx = max3f(__uint_as_float(rr[0]), __uint_as_float(rr[1]), __uint_as_float(rr[0])); }
	s_nop 0
	v_mfma_f32_32x32x16_bf16 v[128:143], v[2:5], v[168:171], v[128:143]
	v_mfma_f32_32x32x16_bf16 v[112:127], v[6:9], v[168:171], v[112:127]
	v_mfma_f32_32x32x16_bf16 v[128:143], v[10:13], v[172:175], v[128:143]
	v_mfma_f32_32x32x16_bf16 v[112:127], v[208:211], v[172:175], v[112:127]
	v_add_u32_e32 v222, s71, v15
	v_add_u32_e32 v216, s71, v240
	v_sub_u32_e32 v223, 0, v216
	v_sub_u32_e32 v224, 0xffffffc0, v222
	v_max_i32_e32 v223, v223, v224
	s_add_i32 s0, s68, -1
	v_sub_u32_e32 v224, s0, v216
	v_sub_u32_e32 v225, 64, v222
	v_min_i32_e32 v224, v224, v225
	v_sub_u32_e32 v224, v224, v223
	v_cmp_gt_i32_e32 vcc, 0, v224
	v_mov_b32_e32 v225, 0x40000000
	v_cndmask_b32_e32 v223, v223, v225, vcc
	v_max_i32_e32 v224, 0, v224
	v_sub_u32_e32 v216, 0, v223
	v_sub_u32_e32 v217, 32, v223
	v_sub_u32_e32 v222, 1, v223
	v_sub_u32_e32 v225, 33, v223
	v_cmp_ge_u32_e32 vcc, v224, v216
	v_cmp_ge_u32_e64 s[0:1], v224, v217
	v_cmp_ge_u32_e64 s[38:39], v224, v222
	v_cmp_ge_u32_e64 s[40:41], v224, v225
	v_cndmask_b32_e32 v128, v220, v128, vcc
	v_cndmask_b32_e64 v112, v220, v112, s[0:1]
	v_cndmask_b32_e64 v129, v220, v129, s[38:39]
	v_cndmask_b32_e64 v113, v220, v113, s[40:41]
	v_sub_u32_e32 v216, 2, v223
	v_sub_u32_e32 v217, 34, v223
	v_sub_u32_e32 v222, 3, v223
	v_sub_u32_e32 v225, 35, v223
	v_cmp_ge_u32_e32 vcc, v224, v216
	v_cmp_ge_u32_e64 s[0:1], v224, v217
	v_cmp_ge_u32_e64 s[38:39], v224, v222
	v_cmp_ge_u32_e64 s[40:41], v224, v225
	v_cndmask_b32_e32 v130, v220, v130, vcc
	v_cndmask_b32_e64 v114, v220, v114, s[0:1]
	v_cndmask_b32_e64 v131, v220, v131, s[38:39]
	v_cndmask_b32_e64 v115, v220, v115, s[40:41]
	v_sub_u32_e32 v216, 8, v223
	v_sub_u32_e32 v217, 40, v223
	v_sub_u32_e32 v222, 9, v223
	v_sub_u32_e32 v225, 41, v223
	v_cmp_ge_u32_e32 vcc, v224, v216
	v_cmp_ge_u32_e64 s[0:1], v224, v217
	v_cmp_ge_u32_e64 s[38:39], v224, v222
	v_cmp_ge_u32_e64 s[40:41], v224, v225
	v_cndmask_b32_e32 v132, v220, v132, vcc
	v_cndmask_b32_e64 v116, v220, v116, s[0:1]
	v_cndmask_b32_e64 v133, v220, v133, s[38:39]
	v_cndmask_b32_e64 v117, v220, v117, s[40:41]
	v_sub_u32_e32 v216, 10, v223
	v_sub_u32_e32 v217, 42, v223
	v_sub_u32_e32 v222, 11, v223
	v_sub_u32_e32 v225, 43, v223
	v_cmp_ge_u32_e32 vcc, v224, v216
	v_cmp_ge_u32_e64 s[0:1], v224, v217
	v_cmp_ge_u32_e64 s[38:39], v224, v222
	v_cmp_ge_u32_e64 s[40:41], v224, v225
	v_cndmask_b32_e32 v134, v220, v134, vcc
	v_cndmask_b32_e64 v118, v220, v118, s[0:1]
	v_cndmask_b32_e64 v135, v220, v135, s[38:39]
	v_cndmask_b32_e64 v119, v220, v119, s[40:41]
	v_sub_u32_e32 v216, 16, v223
	v_sub_u32_e32 v217, 48, v223
	v_sub_u32_e32 v222, 17, v223
	v_sub_u32_e32 v225, 49, v223
	v_cmp_ge_u32_e32 vcc, v224, v216
	v_cmp_ge_u32_e64 s[0:1], v224, v217
	v_cmp_ge_u32_e64 s[38:39], v224, v222
	v_cmp_ge_u32_e64 s[40:41], v224, v225
	v_cndmask_b32_e32 v136, v220, v136, vcc
	v_cndmask_b32_e64 v120, v220, v120, s[0:1]
	v_cndmask_b32_e64 v137, v220, v137, s[38:39]
	v_cndmask_b32_e64 v121, v220, v121, s[40:41]
	v_sub_u32_e32 v216, 18, v223
	v_sub_u32_e32 v217, 50, v223
	v_sub_u32_e32 v222, 19, v223
	v_sub_u32_e32 v225, 51, v223
	v_cmp_ge_u32_e32 vcc, v224, v216
	v_cmp_ge_u32_e64 s[0:1], v224, v217
	v_cmp_ge_u32_e64 s[38:39], v224, v222
	v_cmp_ge_u32_e64 s[40:41], v224, v225
	v_cndmask_b32_e32 v138, v220, v138, vcc
	v_cndmask_b32_e64 v122, v220, v122, s[0:1]
	v_cndmask_b32_e64 v139, v220, v139, s[38:39]
	v_cndmask_b32_e64 v123, v220, v123, s[40:41]
	v_sub_u32_e32 v216, 24, v223
	v_sub_u32_e32 v217, 56, v223
	v_sub_u32_e32 v222, 25, v223
	v_sub_u32_e32 v225, 57, v223
	v_cmp_ge_u32_e32 vcc, v224, v216
	v_cmp_ge_u32_e64 s[0:1], v224, v217
	v_cmp_ge_u32_e64 s[38:39], v224, v222
	v_cmp_ge_u32_e64 s[40:41], v224, v225
	v_cndmask_b32_e32 v140, v220, v140, vcc
	v_cndmask_b32_e64 v124, v220, v124, s[0:1]
	v_cndmask_b32_e64 v141, v220, v141, s[38:39]
	v_cndmask_b32_e64 v125, v220, v125, s[40:41]
	v_sub_u32_e32 v216, 26, v223
	v_sub_u32_e32 v217, 58, v223
	v_sub_u32_e32 v222, 27, v223
	v_sub_u32_e32 v225, 59, v223
	v_cmp_ge_u32_e32 vcc, v224, v216
	v_cmp_ge_u32_e64 s[0:1], v224, v217
	v_cmp_ge_u32_e64 s[38:39], v224, v222
	v_cmp_ge_u32_e64 s[40:41], v224, v225
	v_cndmask_b32_e32 v142, v220, v142, vcc
	v_cndmask_b32_e64 v126, v220, v126, s[0:1]
	v_cndmask_b32_e64 v143, v220, v143, s[38:39]
	v_cndmask_b32_e64 v127, v220, v127, s[40:41]
	v_max3_f32 v216, v128, v112, v129
	ds_read_b64_tr_b16 v[208:209], v241 offset:0
	ds_read_b64_tr_b16 v[210:211], v241 offset:2560
	v_max3_f32 v216, v216, v113, v130
	ds_read_b64_tr_b16 v[10:11], v241 offset:5120
	v_max3_f32 v216, v216, v114, v131
	ds_read_b64_tr_b16 v[12:13], v241 offset:7680
	v_max3_f32 v216, v216, v115, v132
	v_max3_f32 v216, v216, v116, v133
	ds_read_b64_tr_b16 v[6:7], v241 offset:10240
	v_max_f32_e32 v217, v127, v127
	v_max3_f32 v216, v216, v117, v134
	ds_read_b64_tr_b16 v[8:9], v241 offset:12800
	ds_read_b64_tr_b16 v[2:3], v241 offset:15360
	ds_read_b64_tr_b16 v[4:5], v241 offset:17920
	s_andn2_b64 vcc, exec, s[58:59]
	v_max3_f32 v216, v216, v118, v135
	s_mov_b64 s[38:39], s[56:57]
	v_max3_f32 v216, v216, v119, v136
	s_nop 0
	v_max3_f32 v216, v216, v120, v137
	s_nop 0
	v_max3_f32 v216, v216, v121, v138
	s_nop 0
	v_max3_f32 v216, v216, v122, v139
	s_nop 0
	v_max3_f32 v216, v216, v123, v140
	s_nop 0
	v_max3_f32 v216, v216, v124, v141
	s_nop 0
	v_max3_f32 v216, v216, v125, v142
	s_nop 0
	v_max3_f32 v216, v216, v126, v143
	s_nop 0
	v_max_f32_e32 v216, v216, v216
	v_max_f32_e32 v216, v216, v217
	v_mov_b32_e32 v217, v216
	s_nop 1
	v_permlane32_swap_b32_e32 v216, v217
	v_max3_f32 v242, v216, v217, v216
	v_cndmask_b32_e64 v216, 0, 1, s[58:59]
	v_cmp_ne_u32_e64 s[0:1], 1, v216
	s_cbranch_vccnz .LBB0_311
	v_cmp_lt_f32_e32 vcc, s29, v242
	s_cmp_lg_u64 vcc, 0
	s_cselect_b64 s[38:39], -1, 0
